# v7 + drop redundant post-barrier lgkmcnt(0) and merge the pre-barrier vmcnt/lgkmcnt waits in K-loops
# baseline (speedup 1.0000x reference)
.LBB0_109:
	ds_read_b128 v[130:133], v158
	ds_read_b128 v[162:165], v158 offset:1024
	ds_read_b128 v[166:169], v158 offset:2048
	ds_read_b128 v[170:173], v158 offset:3072
	ds_read_b128 v[174:177], v159
	ds_read_b128 v[178:181], v159 offset:1024
	ds_read_b128 v[182:185], v159 offset:2048
	ds_read_b128 v[186:189], v159 offset:3072
	s_add_u32 s22, s20, 0xfff04000
	s_addc_u32 s23, s21, -1
	s_cmp_eq_u32 s46, 60
	s_cselect_b32 s26, s42, s22
	s_cselect_b32 s27, s15, s23
	s_cselect_b32 s24, s43, s44
	s_cselect_b32 s25, s13, s45
	s_add_u32 s22, s26, 0x4000
	s_addc_u32 s23, s27, 0
	s_add_i32 m0, s29, 0xc000
	ds_read_b128 v[190:193], v160
	ds_read_b128 v[194:197], v160 offset:1024
	ds_read_b128 v[198:201], v160 offset:2048
	ds_read_b128 v[202:205], v160 offset:3072
	ds_read_b128 v[206:209], v160 offset:4096
	ds_read_b128 v[210:213], v160 offset:5120
	ds_read_b128 v[214:217], v160 offset:6144
	ds_read_b128 v[218:221], v160 offset:7168
	global_load_lds_dwordx4 v146, s[20:21]
	s_add_i32 m0, s29, 0xe000
	s_nop 0
	global_load_lds_dwordx4 v148, s[20:21]
	s_waitcnt vmcnt(8) lgkmcnt(0)
	s_barrier
	v_mfma_f32_16x16x32_bf16 v[62:65], v[130:133], v[190:193], v[62:65]
	v_mfma_f32_16x16x32_bf16 v[62:65], v[162:165], v[194:197], v[62:65]
	v_mfma_f32_16x16x32_bf16 v[58:61], v[166:169], v[190:193], v[58:61]
	v_mfma_f32_16x16x32_bf16 v[58:61], v[170:173], v[194:197], v[58:61]
	v_mfma_f32_16x16x32_bf16 v[54:57], v[130:133], v[198:201], v[54:57]
	v_mfma_f32_16x16x32_bf16 v[54:57], v[162:165], v[202:205], v[54:57]
	v_mfma_f32_16x16x32_bf16 v[50:53], v[166:169], v[198:201], v[50:53]
	v_mfma_f32_16x16x32_bf16 v[50:53], v[170:173], v[202:205], v[50:53]
	v_mfma_f32_16x16x32_bf16 v[46:49], v[130:133], v[206:209], v[46:49]
	v_mfma_f32_16x16x32_bf16 v[46:49], v[162:165], v[210:213], v[46:49]
	v_mfma_f32_16x16x32_bf16 v[42:45], v[166:169], v[206:209], v[42:45]
	v_mfma_f32_16x16x32_bf16 v[42:45], v[170:173], v[210:213], v[42:45]
	v_mfma_f32_16x16x32_bf16 v[38:41], v[130:133], v[214:217], v[38:41]
	v_mfma_f32_16x16x32_bf16 v[38:41], v[162:165], v[218:221], v[38:41]
	v_mfma_f32_16x16x32_bf16 v[34:37], v[166:169], v[214:217], v[34:37]
	v_mfma_f32_16x16x32_bf16 v[34:37], v[170:173], v[218:221], v[34:37]
	v_mfma_f32_16x16x32_bf16 v[126:129], v[174:177], v[190:193], v[126:129]
	v_mfma_f32_16x16x32_bf16 v[126:129], v[178:181], v[194:197], v[126:129]
	v_mfma_f32_16x16x32_bf16 v[122:125], v[182:185], v[190:193], v[122:125]
	v_mfma_f32_16x16x32_bf16 v[122:125], v[186:189], v[194:197], v[122:125]
	v_mfma_f32_16x16x32_bf16 v[118:121], v[174:177], v[198:201], v[118:121]
	v_mfma_f32_16x16x32_bf16 v[118:121], v[178:181], v[202:205], v[118:121]
	v_mfma_f32_16x16x32_bf16 v[114:117], v[182:185], v[198:201], v[114:117]
	v_mfma_f32_16x16x32_bf16 v[114:117], v[186:189], v[202:205], v[114:117]
	v_mfma_f32_16x16x32_bf16 v[110:113], v[174:177], v[206:209], v[110:113]
	v_mfma_f32_16x16x32_bf16 v[110:113], v[178:181], v[210:213], v[110:113]
	v_mfma_f32_16x16x32_bf16 v[106:109], v[182:185], v[206:209], v[106:109]
	v_mfma_f32_16x16x32_bf16 v[106:109], v[186:189], v[210:213], v[106:109]
	v_mfma_f32_16x16x32_bf16 v[102:105], v[174:177], v[214:217], v[102:105]
	v_mfma_f32_16x16x32_bf16 v[102:105], v[178:181], v[218:221], v[102:105]
	v_mfma_f32_16x16x32_bf16 v[98:101], v[182:185], v[214:217], v[98:101]
	v_mfma_f32_16x16x32_bf16 v[98:101], v[186:189], v[218:221], v[98:101]
	s_barrier
	s_add_i32 s47, s36, s28
	s_mov_b32 m0, s47
	ds_read_b128 v[190:193], v160 offset:16384
	ds_read_b128 v[194:197], v160 offset:17408
	ds_read_b128 v[198:201], v160 offset:18432
	ds_read_b128 v[202:205], v160 offset:19456
	ds_read_b128 v[206:209], v160 offset:20480
	ds_read_b128 v[210:213], v160 offset:21504
	ds_read_b128 v[214:217], v160 offset:22528
	ds_read_b128 v[218:221], v160 offset:23552
	global_load_lds_dwordx4 v138, s[24:25]
	s_add_i32 m0, s47, 0x2000
	s_add_u32 s48, s24, 0x100000
	s_addc_u32 s49, s25, 0
	s_add_i32 s47, s37, s28
	global_load_lds_dwordx4 v134, s[24:25]
	s_mov_b32 m0, s47
	s_nop 0
	global_load_lds_dwordx4 v138, s[48:49]
	s_add_i32 m0, s47, 0x2000
	s_nop 0
	global_load_lds_dwordx4 v134, s[48:49]
	s_mov_b32 m0, s29
	s_nop 0
	global_load_lds_dwordx4 v140, s[26:27]
	s_mov_b32 m0, s30
	s_nop 0
	global_load_lds_dwordx4 v136, s[26:27]
	s_waitcnt vmcnt(8) lgkmcnt(0)
	s_barrier
	v_mfma_f32_16x16x32_bf16 v[30:33], v[130:133], v[190:193], v[30:33]
	v_mfma_f32_16x16x32_bf16 v[30:33], v[162:165], v[194:197], v[30:33]
	v_mfma_f32_16x16x32_bf16 v[26:29], v[166:169], v[190:193], v[26:29]
	v_mfma_f32_16x16x32_bf16 v[26:29], v[170:173], v[194:197], v[26:29]
	v_mfma_f32_16x16x32_bf16 v[22:25], v[130:133], v[198:201], v[22:25]
	v_mfma_f32_16x16x32_bf16 v[22:25], v[162:165], v[202:205], v[22:25]
	v_mfma_f32_16x16x32_bf16 v[18:21], v[166:169], v[198:201], v[18:21]
	v_mfma_f32_16x16x32_bf16 v[18:21], v[170:173], v[202:205], v[18:21]
	v_mfma_f32_16x16x32_bf16 v[14:17], v[130:133], v[206:209], v[14:17]
	v_mfma_f32_16x16x32_bf16 v[14:17], v[162:165], v[210:213], v[14:17]
	v_mfma_f32_16x16x32_bf16 v[10:13], v[166:169], v[206:209], v[10:13]
	v_mfma_f32_16x16x32_bf16 v[10:13], v[170:173], v[210:213], v[10:13]
	v_mfma_f32_16x16x32_bf16 v[6:9], v[130:133], v[214:217], v[6:9]
	v_mfma_f32_16x16x32_bf16 v[6:9], v[162:165], v[218:221], v[6:9]
	v_mfma_f32_16x16x32_bf16 v[2:5], v[166:169], v[214:217], v[2:5]
	v_mfma_f32_16x16x32_bf16 v[2:5], v[170:173], v[218:221], v[2:5]
	v_mfma_f32_16x16x32_bf16 v[94:97], v[174:177], v[190:193], v[94:97]
	v_mfma_f32_16x16x32_bf16 v[94:97], v[178:181], v[194:197], v[94:97]
	v_mfma_f32_16x16x32_bf16 v[90:93], v[182:185], v[190:193], v[90:93]
	v_mfma_f32_16x16x32_bf16 v[90:93], v[186:189], v[194:197], v[90:93]
	v_mfma_f32_16x16x32_bf16 v[86:89], v[174:177], v[198:201], v[86:89]
	v_mfma_f32_16x16x32_bf16 v[86:89], v[178:181], v[202:205], v[86:89]
	v_mfma_f32_16x16x32_bf16 v[82:85], v[182:185], v[198:201], v[82:85]
	v_mfma_f32_16x16x32_bf16 v[82:85], v[186:189], v[202:205], v[82:85]
	v_mfma_f32_16x16x32_bf16 v[78:81], v[174:177], v[206:209], v[78:81]
	v_mfma_f32_16x16x32_bf16 v[78:81], v[178:181], v[210:213], v[78:81]
	v_mfma_f32_16x16x32_bf16 v[74:77], v[182:185], v[206:209], v[74:77]
	v_mfma_f32_16x16x32_bf16 v[74:77], v[186:189], v[210:213], v[74:77]
	v_mfma_f32_16x16x32_bf16 v[70:73], v[174:177], v[214:217], v[70:73]
	v_mfma_f32_16x16x32_bf16 v[70:73], v[178:181], v[218:221], v[70:73]
	v_mfma_f32_16x16x32_bf16 v[66:69], v[182:185], v[214:217], v[66:69]
	v_mfma_f32_16x16x32_bf16 v[66:69], v[186:189], v[218:221], v[66:69]
	s_barrier
	s_add_i32 s47, 0, 0x18000
	v_add_u32_e32 v154, s47, v156
	s_add_i32 s48, 0, 0x1c000
	ds_read_b128 v[130:133], v154
	ds_read_b128 v[162:165], v154 offset:1024
	ds_read_b128 v[166:169], v154 offset:2048
	ds_read_b128 v[170:173], v154 offset:3072
	v_add_u32_e32 v154, s48, v156
	ds_read_b128 v[174:177], v154
	ds_read_b128 v[178:181], v154 offset:1024
	ds_read_b128 v[182:185], v154 offset:2048
	ds_read_b128 v[186:189], v154 offset:3072
	s_add_u32 s26, s26, 0x100000
	s_addc_u32 s27, s27, 0
	s_mov_b32 m0, s31
	ds_read_b128 v[190:193], v160 offset:32768
	ds_read_b128 v[194:197], v160 offset:33792
	ds_read_b128 v[198:201], v160 offset:34816
	ds_read_b128 v[202:205], v160 offset:35840
	ds_read_b128 v[206:209], v160 offset:36864
	ds_read_b128 v[210:213], v160 offset:37888
	ds_read_b128 v[214:217], v160 offset:38912
	ds_read_b128 v[218:221], v160 offset:39936
	global_load_lds_dwordx4 v140, s[26:27]
	s_mov_b32 m0, s33
	s_nop 0
	global_load_lds_dwordx4 v136, s[26:27]
	s_waitcnt vmcnt(8) lgkmcnt(0)
	s_barrier
	v_mfma_f32_16x16x32_bf16 v[62:65], v[130:133], v[190:193], v[62:65]
	v_mfma_f32_16x16x32_bf16 v[62:65], v[162:165], v[194:197], v[62:65]
	v_mfma_f32_16x16x32_bf16 v[58:61], v[166:169], v[190:193], v[58:61]
	v_mfma_f32_16x16x32_bf16 v[58:61], v[170:173], v[194:197], v[58:61]
	v_mfma_f32_16x16x32_bf16 v[54:57], v[130:133], v[198:201], v[54:57]
	v_mfma_f32_16x16x32_bf16 v[54:57], v[162:165], v[202:205], v[54:57]
	v_mfma_f32_16x16x32_bf16 v[50:53], v[166:169], v[198:201], v[50:53]
	v_mfma_f32_16x16x32_bf16 v[50:53], v[170:173], v[202:205], v[50:53]
	v_mfma_f32_16x16x32_bf16 v[46:49], v[130:133], v[206:209], v[46:49]
	v_mfma_f32_16x16x32_bf16 v[46:49], v[162:165], v[210:213], v[46:49]
	v_mfma_f32_16x16x32_bf16 v[42:45], v[166:169], v[206:209], v[42:45]
	v_mfma_f32_16x16x32_bf16 v[42:45], v[170:173], v[210:213], v[42:45]
	v_mfma_f32_16x16x32_bf16 v[38:41], v[130:133], v[214:217], v[38:41]
	v_mfma_f32_16x16x32_bf16 v[38:41], v[162:165], v[218:221], v[38:41]
	v_mfma_f32_16x16x32_bf16 v[34:37], v[166:169], v[214:217], v[34:37]
	v_mfma_f32_16x16x32_bf16 v[34:37], v[170:173], v[218:221], v[34:37]
	v_mfma_f32_16x16x32_bf16 v[126:129], v[174:177], v[190:193], v[126:129]
	v_mfma_f32_16x16x32_bf16 v[126:129], v[178:181], v[194:197], v[126:129]
	v_mfma_f32_16x16x32_bf16 v[122:125], v[182:185], v[190:193], v[122:125]
	v_mfma_f32_16x16x32_bf16 v[122:125], v[186:189], v[194:197], v[122:125]
	v_mfma_f32_16x16x32_bf16 v[118:121], v[174:177], v[198:201], v[118:121]
	v_mfma_f32_16x16x32_bf16 v[118:121], v[178:181], v[202:205], v[118:121]
	v_mfma_f32_16x16x32_bf16 v[114:117], v[182:185], v[198:201], v[114:117]
	v_mfma_f32_16x16x32_bf16 v[114:117], v[186:189], v[202:205], v[114:117]
	v_mfma_f32_16x16x32_bf16 v[110:113], v[174:177], v[206:209], v[110:113]
	v_mfma_f32_16x16x32_bf16 v[110:113], v[178:181], v[210:213], v[110:113]
	v_mfma_f32_16x16x32_bf16 v[106:109], v[182:185], v[206:209], v[106:109]
	v_mfma_f32_16x16x32_bf16 v[106:109], v[186:189], v[210:213], v[106:109]
	v_mfma_f32_16x16x32_bf16 v[102:105], v[174:177], v[214:217], v[102:105]
	v_mfma_f32_16x16x32_bf16 v[102:105], v[178:181], v[218:221], v[102:105]
	v_mfma_f32_16x16x32_bf16 v[98:101], v[182:185], v[214:217], v[98:101]
	v_mfma_f32_16x16x32_bf16 v[98:101], v[186:189], v[218:221], v[98:101]
	s_barrier
	s_add_u32 s26, s24, 0x4000
	s_addc_u32 s27, s25, 0
	s_add_i32 s47, s47, s28
	s_mov_b32 m0, s47
	ds_read_b128 v[190:193], v160 offset:49152
	ds_read_b128 v[194:197], v160 offset:50176
	ds_read_b128 v[198:201], v160 offset:51200
	ds_read_b128 v[202:205], v160 offset:52224
	ds_read_b128 v[206:209], v160 offset:53248
	ds_read_b128 v[210:213], v160 offset:54272
	ds_read_b128 v[214:217], v160 offset:55296
	ds_read_b128 v[218:221], v160 offset:56320
	global_load_lds_dwordx4 v138, s[26:27]
	s_add_i32 m0, s47, 0x2000
	s_add_u32 s24, s24, 0x104000
	s_addc_u32 s25, s25, 0
	global_load_lds_dwordx4 v134, s[26:27]
	s_add_i32 s26, s48, s28
	s_mov_b32 m0, s26
	s_nop 0
	global_load_lds_dwordx4 v138, s[24:25]
	s_add_i32 m0, s26, 0x2000
	s_nop 0
	global_load_lds_dwordx4 v134, s[24:25]
	s_mov_b32 m0, s34
	s_nop 0
	global_load_lds_dwordx4 v140, s[22:23]
	s_mov_b32 m0, s35
	s_nop 0
	global_load_lds_dwordx4 v136, s[22:23]
	s_waitcnt vmcnt(8) lgkmcnt(0)
	s_barrier
	v_mfma_f32_16x16x32_bf16 v[30:33], v[130:133], v[190:193], v[30:33]
	v_mfma_f32_16x16x32_bf16 v[30:33], v[162:165], v[194:197], v[30:33]
	v_mfma_f32_16x16x32_bf16 v[26:29], v[166:169], v[190:193], v[26:29]
	v_mfma_f32_16x16x32_bf16 v[26:29], v[170:173], v[194:197], v[26:29]
	v_mfma_f32_16x16x32_bf16 v[22:25], v[130:133], v[198:201], v[22:25]
	v_mfma_f32_16x16x32_bf16 v[22:25], v[162:165], v[202:205], v[22:25]
	v_mfma_f32_16x16x32_bf16 v[18:21], v[166:169], v[198:201], v[18:21]
	v_mfma_f32_16x16x32_bf16 v[18:21], v[170:173], v[202:205], v[18:21]
	v_mfma_f32_16x16x32_bf16 v[14:17], v[130:133], v[206:209], v[14:17]
	v_mfma_f32_16x16x32_bf16 v[14:17], v[162:165], v[210:213], v[14:17]
	v_mfma_f32_16x16x32_bf16 v[10:13], v[166:169], v[206:209], v[10:13]
	v_mfma_f32_16x16x32_bf16 v[10:13], v[170:173], v[210:213], v[10:13]
	v_mfma_f32_16x16x32_bf16 v[6:9], v[130:133], v[214:217], v[6:9]
	v_mfma_f32_16x16x32_bf16 v[6:9], v[162:165], v[218:221], v[6:9]
	v_mfma_f32_16x16x32_bf16 v[2:5], v[166:169], v[214:217], v[2:5]
	v_mfma_f32_16x16x32_bf16 v[2:5], v[170:173], v[218:221], v[2:5]
	v_mfma_f32_16x16x32_bf16 v[94:97], v[174:177], v[190:193], v[94:97]
	v_mfma_f32_16x16x32_bf16 v[94:97], v[178:181], v[194:197], v[94:97]
	v_mfma_f32_16x16x32_bf16 v[90:93], v[182:185], v[190:193], v[90:93]
	v_mfma_f32_16x16x32_bf16 v[90:93], v[186:189], v[194:197], v[90:93]
	v_mfma_f32_16x16x32_bf16 v[86:89], v[174:177], v[198:201], v[86:89]
	v_mfma_f32_16x16x32_bf16 v[86:89], v[178:181], v[202:205], v[86:89]
	v_mfma_f32_16x16x32_bf16 v[82:85], v[182:185], v[198:201], v[82:85]
	v_mfma_f32_16x16x32_bf16 v[82:85], v[186:189], v[202:205], v[82:85]
	v_mfma_f32_16x16x32_bf16 v[78:81], v[174:177], v[206:209], v[78:81]
	v_mfma_f32_16x16x32_bf16 v[78:81], v[178:181], v[210:213], v[78:81]
	v_mfma_f32_16x16x32_bf16 v[74:77], v[182:185], v[206:209], v[74:77]
	v_mfma_f32_16x16x32_bf16 v[74:77], v[186:189], v[210:213], v[74:77]
	v_mfma_f32_16x16x32_bf16 v[70:73], v[174:177], v[214:217], v[70:73]
	v_mfma_f32_16x16x32_bf16 v[70:73], v[178:181], v[218:221], v[70:73]
	v_mfma_f32_16x16x32_bf16 v[66:69], v[182:185], v[214:217], v[66:69]
	v_mfma_f32_16x16x32_bf16 v[66:69], v[186:189], v[218:221], v[66:69]
	s_barrier
	s_add_i32 s46, s46, 2
	s_add_u32 s20, s20, 0x8000
	s_addc_u32 s21, s21, 0
	s_add_u32 s44, s44, 0x8000
	s_addc_u32 s45, s45, 0
	s_cmp_gt_u32 s46, 61
	s_cbranch_scc0 .LBB0_109
	s_and_b64 vcc, exec, s[8:9]
	s_cbranch_vccnz .LBB0_113
	v_lshl_add_u32 v154, s4, 8, v1
	s_cmp_lg_u32 s41, 24
	s_mov_b64 s[20:21], -1
	s_cbranch_scc1 .LBB0_114

.LBB0_376:
	ds_read_b128 v[130:133], v159
	ds_read_b128 v[162:165], v159 offset:1024
	ds_read_b128 v[166:169], v159 offset:2048
	ds_read_b128 v[170:173], v159 offset:3072
	ds_read_b128 v[174:177], v160
	ds_read_b128 v[178:181], v160 offset:1024
	ds_read_b128 v[182:185], v160 offset:2048
	ds_read_b128 v[186:189], v160 offset:3072
	s_add_u32 s34, s26, 0xfff04000
	s_addc_u32 s35, s27, -1
	s_cmp_eq_u32 s87, 60
	s_cselect_b32 s38, s80, s34
	s_cselect_b32 s39, s21, s35
	s_cselect_b32 s36, s81, s83
	s_cselect_b32 s37, s19, s86
	s_add_u32 s34, s38, 0x4000
	s_addc_u32 s35, s39, 0
	s_add_i32 m0, s46, 0xc000
	ds_read_b128 v[190:193], v161
	ds_read_b128 v[194:197], v161 offset:1024
	ds_read_b128 v[198:201], v161 offset:2048
	ds_read_b128 v[202:205], v161 offset:3072
	ds_read_b128 v[206:209], v161 offset:4096
	ds_read_b128 v[210:213], v161 offset:5120
	ds_read_b128 v[214:217], v161 offset:6144
	ds_read_b128 v[218:221], v161 offset:7168
	global_load_lds_dwordx4 v146, s[26:27]
	s_add_i32 m0, s46, 0xe000
	s_nop 0
	global_load_lds_dwordx4 v148, s[26:27]
	s_waitcnt vmcnt(8) lgkmcnt(0)
	s_barrier
	v_mfma_f32_16x16x32_bf16 v[62:65], v[130:133], v[190:193], v[62:65]
	v_mfma_f32_16x16x32_bf16 v[62:65], v[162:165], v[194:197], v[62:65]
	v_mfma_f32_16x16x32_bf16 v[58:61], v[166:169], v[190:193], v[58:61]
	v_mfma_f32_16x16x32_bf16 v[58:61], v[170:173], v[194:197], v[58:61]
	v_mfma_f32_16x16x32_bf16 v[54:57], v[130:133], v[198:201], v[54:57]
	v_mfma_f32_16x16x32_bf16 v[54:57], v[162:165], v[202:205], v[54:57]
	v_mfma_f32_16x16x32_bf16 v[50:53], v[166:169], v[198:201], v[50:53]
	v_mfma_f32_16x16x32_bf16 v[50:53], v[170:173], v[202:205], v[50:53]
	v_mfma_f32_16x16x32_bf16 v[46:49], v[130:133], v[206:209], v[46:49]
	v_mfma_f32_16x16x32_bf16 v[46:49], v[162:165], v[210:213], v[46:49]
	v_mfma_f32_16x16x32_bf16 v[42:45], v[166:169], v[206:209], v[42:45]
	v_mfma_f32_16x16x32_bf16 v[42:45], v[170:173], v[210:213], v[42:45]
	v_mfma_f32_16x16x32_bf16 v[38:41], v[130:133], v[214:217], v[38:41]
	v_mfma_f32_16x16x32_bf16 v[38:41], v[162:165], v[218:221], v[38:41]
	v_mfma_f32_16x16x32_bf16 v[34:37], v[166:169], v[214:217], v[34:37]
	v_mfma_f32_16x16x32_bf16 v[34:37], v[170:173], v[218:221], v[34:37]
	v_mfma_f32_16x16x32_bf16 v[126:129], v[174:177], v[190:193], v[126:129]
	v_mfma_f32_16x16x32_bf16 v[126:129], v[178:181], v[194:197], v[126:129]
	v_mfma_f32_16x16x32_bf16 v[122:125], v[182:185], v[190:193], v[122:125]
	v_mfma_f32_16x16x32_bf16 v[122:125], v[186:189], v[194:197], v[122:125]
	v_mfma_f32_16x16x32_bf16 v[118:121], v[174:177], v[198:201], v[118:121]
	v_mfma_f32_16x16x32_bf16 v[118:121], v[178:181], v[202:205], v[118:121]
	v_mfma_f32_16x16x32_bf16 v[114:117], v[182:185], v[198:201], v[114:117]
	v_mfma_f32_16x16x32_bf16 v[114:117], v[186:189], v[202:205], v[114:117]
	v_mfma_f32_16x16x32_bf16 v[110:113], v[174:177], v[206:209], v[110:113]
	v_mfma_f32_16x16x32_bf16 v[110:113], v[178:181], v[210:213], v[110:113]
	v_mfma_f32_16x16x32_bf16 v[106:109], v[182:185], v[206:209], v[106:109]
	v_mfma_f32_16x16x32_bf16 v[106:109], v[186:189], v[210:213], v[106:109]
	v_mfma_f32_16x16x32_bf16 v[102:105], v[174:177], v[214:217], v[102:105]
	v_mfma_f32_16x16x32_bf16 v[102:105], v[178:181], v[218:221], v[102:105]
	v_mfma_f32_16x16x32_bf16 v[98:101], v[182:185], v[214:217], v[98:101]
	v_mfma_f32_16x16x32_bf16 v[98:101], v[186:189], v[218:221], v[98:101]
	s_barrier
	s_add_i32 s88, s66, s41
	s_mov_b32 m0, s88
	ds_read_b128 v[190:193], v161 offset:16384
	ds_read_b128 v[194:197], v161 offset:17408
	ds_read_b128 v[198:201], v161 offset:18432
	ds_read_b128 v[202:205], v161 offset:19456
	ds_read_b128 v[206:209], v161 offset:20480
	ds_read_b128 v[210:213], v161 offset:21504
	ds_read_b128 v[214:217], v161 offset:22528
	ds_read_b128 v[218:221], v161 offset:23552
	global_load_lds_dwordx4 v138, s[36:37]
	s_add_i32 m0, s88, 0x2000
	s_add_u32 s88, s36, 0x100000
	s_addc_u32 s89, s37, 0
	s_add_i32 vcc_lo, s67, s41
	global_load_lds_dwordx4 v134, s[36:37]
	s_mov_b32 m0, vcc_lo
	s_nop 0
	global_load_lds_dwordx4 v138, s[88:89]
	s_add_i32 m0, vcc_lo, 0x2000
	s_nop 0
	global_load_lds_dwordx4 v134, s[88:89]
	s_mov_b32 m0, s46
	s_nop 0
	global_load_lds_dwordx4 v140, s[38:39]
	s_mov_b32 m0, s47
	s_nop 0
	global_load_lds_dwordx4 v136, s[38:39]
	s_waitcnt vmcnt(8) lgkmcnt(0)
	s_barrier
	v_mfma_f32_16x16x32_bf16 v[30:33], v[130:133], v[190:193], v[30:33]
	v_mfma_f32_16x16x32_bf16 v[30:33], v[162:165], v[194:197], v[30:33]
	v_mfma_f32_16x16x32_bf16 v[26:29], v[166:169], v[190:193], v[26:29]
	v_mfma_f32_16x16x32_bf16 v[26:29], v[170:173], v[194:197], v[26:29]
	v_mfma_f32_16x16x32_bf16 v[22:25], v[130:133], v[198:201], v[22:25]
	v_mfma_f32_16x16x32_bf16 v[22:25], v[162:165], v[202:205], v[22:25]
	v_mfma_f32_16x16x32_bf16 v[18:21], v[166:169], v[198:201], v[18:21]
	v_mfma_f32_16x16x32_bf16 v[18:21], v[170:173], v[202:205], v[18:21]
	v_mfma_f32_16x16x32_bf16 v[14:17], v[130:133], v[206:209], v[14:17]
	v_mfma_f32_16x16x32_bf16 v[14:17], v[162:165], v[210:213], v[14:17]
	v_mfma_f32_16x16x32_bf16 v[10:13], v[166:169], v[206:209], v[10:13]
	v_mfma_f32_16x16x32_bf16 v[10:13], v[170:173], v[210:213], v[10:13]
	v_mfma_f32_16x16x32_bf16 v[6:9], v[130:133], v[214:217], v[6:9]
	v_mfma_f32_16x16x32_bf16 v[6:9], v[162:165], v[218:221], v[6:9]
	v_mfma_f32_16x16x32_bf16 v[2:5], v[166:169], v[214:217], v[2:5]
	v_mfma_f32_16x16x32_bf16 v[2:5], v[170:173], v[218:221], v[2:5]
	v_mfma_f32_16x16x32_bf16 v[94:97], v[174:177], v[190:193], v[94:97]
	v_mfma_f32_16x16x32_bf16 v[94:97], v[178:181], v[194:197], v[94:97]
	v_mfma_f32_16x16x32_bf16 v[90:93], v[182:185], v[190:193], v[90:93]
	v_mfma_f32_16x16x32_bf16 v[90:93], v[186:189], v[194:197], v[90:93]
	v_mfma_f32_16x16x32_bf16 v[86:89], v[174:177], v[198:201], v[86:89]
	v_mfma_f32_16x16x32_bf16 v[86:89], v[178:181], v[202:205], v[86:89]
	v_mfma_f32_16x16x32_bf16 v[82:85], v[182:185], v[198:201], v[82:85]
	v_mfma_f32_16x16x32_bf16 v[82:85], v[186:189], v[202:205], v[82:85]
	v_mfma_f32_16x16x32_bf16 v[78:81], v[174:177], v[206:209], v[78:81]
	v_mfma_f32_16x16x32_bf16 v[78:81], v[178:181], v[210:213], v[78:81]
	v_mfma_f32_16x16x32_bf16 v[74:77], v[182:185], v[206:209], v[74:77]
	v_mfma_f32_16x16x32_bf16 v[74:77], v[186:189], v[210:213], v[74:77]
	v_mfma_f32_16x16x32_bf16 v[70:73], v[174:177], v[214:217], v[70:73]
	v_mfma_f32_16x16x32_bf16 v[70:73], v[178:181], v[218:221], v[70:73]
	v_mfma_f32_16x16x32_bf16 v[66:69], v[182:185], v[214:217], v[66:69]
	v_mfma_f32_16x16x32_bf16 v[66:69], v[186:189], v[218:221], v[66:69]
	s_barrier
	s_add_i32 s88, 0, 0x18000
	v_add_u32_e32 v154, s88, v157
	s_add_i32 s89, 0, 0x1c000
	ds_read_b128 v[130:133], v154
	ds_read_b128 v[162:165], v154 offset:1024
	ds_read_b128 v[166:169], v154 offset:2048
	ds_read_b128 v[170:173], v154 offset:3072
	v_add_u32_e32 v154, s89, v157
	ds_read_b128 v[174:177], v154
	ds_read_b128 v[178:181], v154 offset:1024
	ds_read_b128 v[182:185], v154 offset:2048
	ds_read_b128 v[186:189], v154 offset:3072
	s_add_u32 s38, s38, 0x100000
	s_addc_u32 s39, s39, 0
	s_mov_b32 m0, s58
	ds_read_b128 v[190:193], v161 offset:32768
	ds_read_b128 v[194:197], v161 offset:33792
	ds_read_b128 v[198:201], v161 offset:34816
	ds_read_b128 v[202:205], v161 offset:35840
	ds_read_b128 v[206:209], v161 offset:36864
	ds_read_b128 v[210:213], v161 offset:37888
	ds_read_b128 v[214:217], v161 offset:38912
	ds_read_b128 v[218:221], v161 offset:39936
	global_load_lds_dwordx4 v140, s[38:39]
	s_mov_b32 m0, s59
	s_nop 0
	global_load_lds_dwordx4 v136, s[38:39]
	s_waitcnt vmcnt(8) lgkmcnt(0)
	s_barrier
	v_mfma_f32_16x16x32_bf16 v[62:65], v[130:133], v[190:193], v[62:65]
	v_mfma_f32_16x16x32_bf16 v[62:65], v[162:165], v[194:197], v[62:65]
	v_mfma_f32_16x16x32_bf16 v[58:61], v[166:169], v[190:193], v[58:61]
	v_mfma_f32_16x16x32_bf16 v[58:61], v[170:173], v[194:197], v[58:61]
	v_mfma_f32_16x16x32_bf16 v[54:57], v[130:133], v[198:201], v[54:57]
	v_mfma_f32_16x16x32_bf16 v[54:57], v[162:165], v[202:205], v[54:57]
	v_mfma_f32_16x16x32_bf16 v[50:53], v[166:169], v[198:201], v[50:53]
	v_mfma_f32_16x16x32_bf16 v[50:53], v[170:173], v[202:205], v[50:53]
	v_mfma_f32_16x16x32_bf16 v[46:49], v[130:133], v[206:209], v[46:49]
	v_mfma_f32_16x16x32_bf16 v[46:49], v[162:165], v[210:213], v[46:49]
	v_mfma_f32_16x16x32_bf16 v[42:45], v[166:169], v[206:209], v[42:45]
	v_mfma_f32_16x16x32_bf16 v[42:45], v[170:173], v[210:213], v[42:45]
	v_mfma_f32_16x16x32_bf16 v[38:41], v[130:133], v[214:217], v[38:41]
	v_mfma_f32_16x16x32_bf16 v[38:41], v[162:165], v[218:221], v[38:41]
	v_mfma_f32_16x16x32_bf16 v[34:37], v[166:169], v[214:217], v[34:37]
	v_mfma_f32_16x16x32_bf16 v[34:37], v[170:173], v[218:221], v[34:37]
	v_mfma_f32_16x16x32_bf16 v[126:129], v[174:177], v[190:193], v[126:129]
	v_mfma_f32_16x16x32_bf16 v[126:129], v[178:181], v[194:197], v[126:129]
	v_mfma_f32_16x16x32_bf16 v[122:125], v[182:185], v[190:193], v[122:125]
	v_mfma_f32_16x16x32_bf16 v[122:125], v[186:189], v[194:197], v[122:125]
	v_mfma_f32_16x16x32_bf16 v[118:121], v[174:177], v[198:201], v[118:121]
	v_mfma_f32_16x16x32_bf16 v[118:121], v[178:181], v[202:205], v[118:121]
	v_mfma_f32_16x16x32_bf16 v[114:117], v[182:185], v[198:201], v[114:117]
	v_mfma_f32_16x16x32_bf16 v[114:117], v[186:189], v[202:205], v[114:117]
	v_mfma_f32_16x16x32_bf16 v[110:113], v[174:177], v[206:209], v[110:113]
	v_mfma_f32_16x16x32_bf16 v[110:113], v[178:181], v[210:213], v[110:113]
	v_mfma_f32_16x16x32_bf16 v[106:109], v[182:185], v[206:209], v[106:109]
	v_mfma_f32_16x16x32_bf16 v[106:109], v[186:189], v[210:213], v[106:109]
	v_mfma_f32_16x16x32_bf16 v[102:105], v[174:177], v[214:217], v[102:105]
	v_mfma_f32_16x16x32_bf16 v[102:105], v[178:181], v[218:221], v[102:105]
	v_mfma_f32_16x16x32_bf16 v[98:101], v[182:185], v[214:217], v[98:101]
	v_mfma_f32_16x16x32_bf16 v[98:101], v[186:189], v[218:221], v[98:101]
	s_barrier
	s_add_u32 s38, s36, 0x4000
	s_addc_u32 s39, s37, 0
	s_add_i32 s88, s88, s41
	s_mov_b32 m0, s88
	ds_read_b128 v[190:193], v161 offset:49152
	ds_read_b128 v[194:197], v161 offset:50176
	ds_read_b128 v[198:201], v161 offset:51200
	ds_read_b128 v[202:205], v161 offset:52224
	ds_read_b128 v[206:209], v161 offset:53248
	ds_read_b128 v[210:213], v161 offset:54272
	ds_read_b128 v[214:217], v161 offset:55296
	ds_read_b128 v[218:221], v161 offset:56320
	global_load_lds_dwordx4 v138, s[38:39]
	s_add_i32 m0, s88, 0x2000
	s_add_u32 s36, s36, 0x104000
	s_addc_u32 s37, s37, 0
	global_load_lds_dwordx4 v134, s[38:39]
	s_add_i32 s38, s89, s41
	s_mov_b32 m0, s38
	s_nop 0
	global_load_lds_dwordx4 v138, s[36:37]
	s_add_i32 m0, s38, 0x2000
	s_nop 0
	global_load_lds_dwordx4 v134, s[36:37]
	s_mov_b32 m0, s64
	s_nop 0
	global_load_lds_dwordx4 v140, s[34:35]
	s_mov_b32 m0, s65
	s_nop 0
	global_load_lds_dwordx4 v136, s[34:35]
	s_waitcnt vmcnt(8) lgkmcnt(0)
	s_barrier
	v_mfma_f32_16x16x32_bf16 v[30:33], v[130:133], v[190:193], v[30:33]
	v_mfma_f32_16x16x32_bf16 v[30:33], v[162:165], v[194:197], v[30:33]
	v_mfma_f32_16x16x32_bf16 v[26:29], v[166:169], v[190:193], v[26:29]
	v_mfma_f32_16x16x32_bf16 v[26:29], v[170:173], v[194:197], v[26:29]
	v_mfma_f32_16x16x32_bf16 v[22:25], v[130:133], v[198:201], v[22:25]
	v_mfma_f32_16x16x32_bf16 v[22:25], v[162:165], v[202:205], v[22:25]
	v_mfma_f32_16x16x32_bf16 v[18:21], v[166:169], v[198:201], v[18:21]
	v_mfma_f32_16x16x32_bf16 v[18:21], v[170:173], v[202:205], v[18:21]
	v_mfma_f32_16x16x32_bf16 v[14:17], v[130:133], v[206:209], v[14:17]
	v_mfma_f32_16x16x32_bf16 v[14:17], v[162:165], v[210:213], v[14:17]
	v_mfma_f32_16x16x32_bf16 v[10:13], v[166:169], v[206:209], v[10:13]
	v_mfma_f32_16x16x32_bf16 v[10:13], v[170:173], v[210:213], v[10:13]
	v_mfma_f32_16x16x32_bf16 v[6:9], v[130:133], v[214:217], v[6:9]
	v_mfma_f32_16x16x32_bf16 v[6:9], v[162:165], v[218:221], v[6:9]
	v_mfma_f32_16x16x32_bf16 v[2:5], v[166:169], v[214:217], v[2:5]
	v_mfma_f32_16x16x32_bf16 v[2:5], v[170:173], v[218:221], v[2:5]
	v_mfma_f32_16x16x32_bf16 v[94:97], v[174:177], v[190:193], v[94:97]
	v_mfma_f32_16x16x32_bf16 v[94:97], v[178:181], v[194:197], v[94:97]
	v_mfma_f32_16x16x32_bf16 v[90:93], v[182:185], v[190:193], v[90:93]
	v_mfma_f32_16x16x32_bf16 v[90:93], v[186:189], v[194:197], v[90:93]
	v_mfma_f32_16x16x32_bf16 v[86:89], v[174:177], v[198:201], v[86:89]
	v_mfma_f32_16x16x32_bf16 v[86:89], v[178:181], v[202:205], v[86:89]
	v_mfma_f32_16x16x32_bf16 v[82:85], v[182:185], v[198:201], v[82:85]
	v_mfma_f32_16x16x32_bf16 v[82:85], v[186:189], v[202:205], v[82:85]
	v_mfma_f32_16x16x32_bf16 v[78:81], v[174:177], v[206:209], v[78:81]
	v_mfma_f32_16x16x32_bf16 v[78:81], v[178:181], v[210:213], v[78:81]
	v_mfma_f32_16x16x32_bf16 v[74:77], v[182:185], v[206:209], v[74:77]
	v_mfma_f32_16x16x32_bf16 v[74:77], v[186:189], v[210:213], v[74:77]
	v_mfma_f32_16x16x32_bf16 v[70:73], v[174:177], v[214:217], v[70:73]
	v_mfma_f32_16x16x32_bf16 v[70:73], v[178:181], v[218:221], v[70:73]
	v_mfma_f32_16x16x32_bf16 v[66:69], v[182:185], v[214:217], v[66:69]
	v_mfma_f32_16x16x32_bf16 v[66:69], v[186:189], v[218:221], v[66:69]
	s_barrier
	s_add_i32 s87, s87, 2
	s_add_u32 s26, s26, 0x8000
	s_addc_u32 s27, s27, 0
	s_add_u32 s83, s83, 0x8000
	s_addc_u32 s86, s86, 0
	s_cmp_gt_u32 s87, 61
	s_cbranch_scc0 .LBB0_376
	s_and_b64 vcc, exec, s[14:15]
	s_cbranch_vccz .LBB0_379
	s_barrier

.LBB0_536:
	ds_read_b128 v[130:133], v159
	ds_read_b128 v[162:165], v159 offset:1024
	ds_read_b128 v[166:169], v159 offset:2048
	ds_read_b128 v[170:173], v159 offset:3072
	ds_read_b128 v[174:177], v160
	ds_read_b128 v[178:181], v160 offset:1024
	ds_read_b128 v[182:185], v160 offset:2048
	ds_read_b128 v[186:189], v160 offset:3072
	s_add_u32 s30, s26, 0xfff04000
	s_addc_u32 s31, s27, -1
	s_cmp_eq_u32 s80, 60
	s_cselect_b32 s36, s74, s30
	s_cselect_b32 s37, s21, s31
	s_cselect_b32 s34, s75, s78
	s_cselect_b32 s35, s19, s79
	s_add_u32 s30, s36, 0x4000
	s_addc_u32 s31, s37, 0
	s_add_i32 m0, s42, 0xc000
	ds_read_b128 v[190:193], v161
	ds_read_b128 v[194:197], v161 offset:1024
	ds_read_b128 v[198:201], v161 offset:2048
	ds_read_b128 v[202:205], v161 offset:3072
	ds_read_b128 v[206:209], v161 offset:4096
	ds_read_b128 v[210:213], v161 offset:5120
	ds_read_b128 v[214:217], v161 offset:6144
	ds_read_b128 v[218:221], v161 offset:7168
	global_load_lds_dwordx4 v146, s[26:27]
	s_add_i32 m0, s42, 0xe000
	s_nop 0
	global_load_lds_dwordx4 v148, s[26:27]
	s_waitcnt vmcnt(8) lgkmcnt(0)
	s_barrier
	v_mfma_f32_16x16x32_bf16 v[62:65], v[130:133], v[190:193], v[62:65]
	v_mfma_f32_16x16x32_bf16 v[62:65], v[162:165], v[194:197], v[62:65]
	v_mfma_f32_16x16x32_bf16 v[58:61], v[166:169], v[190:193], v[58:61]
	v_mfma_f32_16x16x32_bf16 v[58:61], v[170:173], v[194:197], v[58:61]
	v_mfma_f32_16x16x32_bf16 v[54:57], v[130:133], v[198:201], v[54:57]
	v_mfma_f32_16x16x32_bf16 v[54:57], v[162:165], v[202:205], v[54:57]
	v_mfma_f32_16x16x32_bf16 v[50:53], v[166:169], v[198:201], v[50:53]
	v_mfma_f32_16x16x32_bf16 v[50:53], v[170:173], v[202:205], v[50:53]
	v_mfma_f32_16x16x32_bf16 v[46:49], v[130:133], v[206:209], v[46:49]
	v_mfma_f32_16x16x32_bf16 v[46:49], v[162:165], v[210:213], v[46:49]
	v_mfma_f32_16x16x32_bf16 v[42:45], v[166:169], v[206:209], v[42:45]
	v_mfma_f32_16x16x32_bf16 v[42:45], v[170:173], v[210:213], v[42:45]
	v_mfma_f32_16x16x32_bf16 v[38:41], v[130:133], v[214:217], v[38:41]
	v_mfma_f32_16x16x32_bf16 v[38:41], v[162:165], v[218:221], v[38:41]
	v_mfma_f32_16x16x32_bf16 v[34:37], v[166:169], v[214:217], v[34:37]
	v_mfma_f32_16x16x32_bf16 v[34:37], v[170:173], v[218:221], v[34:37]
	v_mfma_f32_16x16x32_bf16 v[126:129], v[174:177], v[190:193], v[126:129]
	v_mfma_f32_16x16x32_bf16 v[126:129], v[178:181], v[194:197], v[126:129]
	v_mfma_f32_16x16x32_bf16 v[122:125], v[182:185], v[190:193], v[122:125]
	v_mfma_f32_16x16x32_bf16 v[122:125], v[186:189], v[194:197], v[122:125]
	v_mfma_f32_16x16x32_bf16 v[118:121], v[174:177], v[198:201], v[118:121]
	v_mfma_f32_16x16x32_bf16 v[118:121], v[178:181], v[202:205], v[118:121]
	v_mfma_f32_16x16x32_bf16 v[114:117], v[182:185], v[198:201], v[114:117]
	v_mfma_f32_16x16x32_bf16 v[114:117], v[186:189], v[202:205], v[114:117]
	v_mfma_f32_16x16x32_bf16 v[110:113], v[174:177], v[206:209], v[110:113]
	v_mfma_f32_16x16x32_bf16 v[110:113], v[178:181], v[210:213], v[110:113]
	v_mfma_f32_16x16x32_bf16 v[106:109], v[182:185], v[206:209], v[106:109]
	v_mfma_f32_16x16x32_bf16 v[106:109], v[186:189], v[210:213], v[106:109]
	v_mfma_f32_16x16x32_bf16 v[102:105], v[174:177], v[214:217], v[102:105]
	v_mfma_f32_16x16x32_bf16 v[102:105], v[178:181], v[218:221], v[102:105]
	v_mfma_f32_16x16x32_bf16 v[98:101], v[182:185], v[214:217], v[98:101]
	v_mfma_f32_16x16x32_bf16 v[98:101], v[186:189], v[218:221], v[98:101]
	s_barrier
	s_add_i32 s81, s62, s38
	s_mov_b32 m0, s81
	ds_read_b128 v[190:193], v161 offset:16384
	ds_read_b128 v[194:197], v161 offset:17408
	ds_read_b128 v[198:201], v161 offset:18432
	ds_read_b128 v[202:205], v161 offset:19456
	ds_read_b128 v[206:209], v161 offset:20480
	ds_read_b128 v[210:213], v161 offset:21504
	ds_read_b128 v[214:217], v161 offset:22528
	ds_read_b128 v[218:221], v161 offset:23552
	global_load_lds_dwordx4 v138, s[34:35]
	s_add_i32 m0, s81, 0x2000
	s_add_u32 s86, s34, 0x100000
	s_addc_u32 s87, s35, 0
	s_add_i32 s81, s63, s38
	global_load_lds_dwordx4 v134, s[34:35]
	s_mov_b32 m0, s81
	s_nop 0
	global_load_lds_dwordx4 v138, s[86:87]
	s_add_i32 m0, s81, 0x2000
	s_nop 0
	global_load_lds_dwordx4 v134, s[86:87]
	s_mov_b32 m0, s42
	s_nop 0
	global_load_lds_dwordx4 v140, s[36:37]
	s_mov_b32 m0, s43
	s_nop 0
	global_load_lds_dwordx4 v136, s[36:37]
	s_waitcnt vmcnt(8) lgkmcnt(0)
	s_barrier
	v_mfma_f32_16x16x32_bf16 v[30:33], v[130:133], v[190:193], v[30:33]
	v_mfma_f32_16x16x32_bf16 v[30:33], v[162:165], v[194:197], v[30:33]
	v_mfma_f32_16x16x32_bf16 v[26:29], v[166:169], v[190:193], v[26:29]
	v_mfma_f32_16x16x32_bf16 v[26:29], v[170:173], v[194:197], v[26:29]
	v_mfma_f32_16x16x32_bf16 v[22:25], v[130:133], v[198:201], v[22:25]
	v_mfma_f32_16x16x32_bf16 v[22:25], v[162:165], v[202:205], v[22:25]
	v_mfma_f32_16x16x32_bf16 v[18:21], v[166:169], v[198:201], v[18:21]
	v_mfma_f32_16x16x32_bf16 v[18:21], v[170:173], v[202:205], v[18:21]
	v_mfma_f32_16x16x32_bf16 v[14:17], v[130:133], v[206:209], v[14:17]
	v_mfma_f32_16x16x32_bf16 v[14:17], v[162:165], v[210:213], v[14:17]
	v_mfma_f32_16x16x32_bf16 v[10:13], v[166:169], v[206:209], v[10:13]
	v_mfma_f32_16x16x32_bf16 v[10:13], v[170:173], v[210:213], v[10:13]
	v_mfma_f32_16x16x32_bf16 v[6:9], v[130:133], v[214:217], v[6:9]
	v_mfma_f32_16x16x32_bf16 v[6:9], v[162:165], v[218:221], v[6:9]
	v_mfma_f32_16x16x32_bf16 v[2:5], v[166:169], v[214:217], v[2:5]
	v_mfma_f32_16x16x32_bf16 v[2:5], v[170:173], v[218:221], v[2:5]
	v_mfma_f32_16x16x32_bf16 v[94:97], v[174:177], v[190:193], v[94:97]
	v_mfma_f32_16x16x32_bf16 v[94:97], v[178:181], v[194:197], v[94:97]
	v_mfma_f32_16x16x32_bf16 v[90:93], v[182:185], v[190:193], v[90:93]
	v_mfma_f32_16x16x32_bf16 v[90:93], v[186:189], v[194:197], v[90:93]
	v_mfma_f32_16x16x32_bf16 v[86:89], v[174:177], v[198:201], v[86:89]
	v_mfma_f32_16x16x32_bf16 v[86:89], v[178:181], v[202:205], v[86:89]
	v_mfma_f32_16x16x32_bf16 v[82:85], v[182:185], v[198:201], v[82:85]
	v_mfma_f32_16x16x32_bf16 v[82:85], v[186:189], v[202:205], v[82:85]
	v_mfma_f32_16x16x32_bf16 v[78:81], v[174:177], v[206:209], v[78:81]
	v_mfma_f32_16x16x32_bf16 v[78:81], v[178:181], v[210:213], v[78:81]
	v_mfma_f32_16x16x32_bf16 v[74:77], v[182:185], v[206:209], v[74:77]
	v_mfma_f32_16x16x32_bf16 v[74:77], v[186:189], v[210:213], v[74:77]
	v_mfma_f32_16x16x32_bf16 v[70:73], v[174:177], v[214:217], v[70:73]
	v_mfma_f32_16x16x32_bf16 v[70:73], v[178:181], v[218:221], v[70:73]
	v_mfma_f32_16x16x32_bf16 v[66:69], v[182:185], v[214:217], v[66:69]
	v_mfma_f32_16x16x32_bf16 v[66:69], v[186:189], v[218:221], v[66:69]
	s_barrier
	s_add_i32 s81, 0, 0x18000
	v_add_u32_e32 v154, s81, v157
	s_add_i32 s83, 0, 0x1c000
	ds_read_b128 v[130:133], v154
	ds_read_b128 v[162:165], v154 offset:1024
	ds_read_b128 v[166:169], v154 offset:2048
	ds_read_b128 v[170:173], v154 offset:3072
	v_add_u32_e32 v154, s83, v157
	ds_read_b128 v[174:177], v154
	ds_read_b128 v[178:181], v154 offset:1024
	ds_read_b128 v[182:185], v154 offset:2048
	ds_read_b128 v[186:189], v154 offset:3072
	s_add_u32 s36, s36, 0x100000
	s_addc_u32 s37, s37, 0
	s_mov_b32 m0, s46
	ds_read_b128 v[190:193], v161 offset:32768
	ds_read_b128 v[194:197], v161 offset:33792
	ds_read_b128 v[198:201], v161 offset:34816
	ds_read_b128 v[202:205], v161 offset:35840
	ds_read_b128 v[206:209], v161 offset:36864
	ds_read_b128 v[210:213], v161 offset:37888
	ds_read_b128 v[214:217], v161 offset:38912
	ds_read_b128 v[218:221], v161 offset:39936
	global_load_lds_dwordx4 v140, s[36:37]
	s_mov_b32 m0, s47
	s_nop 0
	global_load_lds_dwordx4 v136, s[36:37]
	s_waitcnt vmcnt(8) lgkmcnt(0)
	s_barrier
	v_mfma_f32_16x16x32_bf16 v[62:65], v[130:133], v[190:193], v[62:65]
	v_mfma_f32_16x16x32_bf16 v[62:65], v[162:165], v[194:197], v[62:65]
	v_mfma_f32_16x16x32_bf16 v[58:61], v[166:169], v[190:193], v[58:61]
	v_mfma_f32_16x16x32_bf16 v[58:61], v[170:173], v[194:197], v[58:61]
	v_mfma_f32_16x16x32_bf16 v[54:57], v[130:133], v[198:201], v[54:57]
	v_mfma_f32_16x16x32_bf16 v[54:57], v[162:165], v[202:205], v[54:57]
	v_mfma_f32_16x16x32_bf16 v[50:53], v[166:169], v[198:201], v[50:53]
	v_mfma_f32_16x16x32_bf16 v[50:53], v[170:173], v[202:205], v[50:53]
	v_mfma_f32_16x16x32_bf16 v[46:49], v[130:133], v[206:209], v[46:49]
	v_mfma_f32_16x16x32_bf16 v[46:49], v[162:165], v[210:213], v[46:49]
	v_mfma_f32_16x16x32_bf16 v[42:45], v[166:169], v[206:209], v[42:45]
	v_mfma_f32_16x16x32_bf16 v[42:45], v[170:173], v[210:213], v[42:45]
	v_mfma_f32_16x16x32_bf16 v[38:41], v[130:133], v[214:217], v[38:41]
	v_mfma_f32_16x16x32_bf16 v[38:41], v[162:165], v[218:221], v[38:41]
	v_mfma_f32_16x16x32_bf16 v[34:37], v[166:169], v[214:217], v[34:37]
	v_mfma_f32_16x16x32_bf16 v[34:37], v[170:173], v[218:221], v[34:37]
	v_mfma_f32_16x16x32_bf16 v[126:129], v[174:177], v[190:193], v[126:129]
	v_mfma_f32_16x16x32_bf16 v[126:129], v[178:181], v[194:197], v[126:129]
	v_mfma_f32_16x16x32_bf16 v[122:125], v[182:185], v[190:193], v[122:125]
	v_mfma_f32_16x16x32_bf16 v[122:125], v[186:189], v[194:197], v[122:125]
	v_mfma_f32_16x16x32_bf16 v[118:121], v[174:177], v[198:201], v[118:121]
	v_mfma_f32_16x16x32_bf16 v[118:121], v[178:181], v[202:205], v[118:121]
	v_mfma_f32_16x16x32_bf16 v[114:117], v[182:185], v[198:201], v[114:117]
	v_mfma_f32_16x16x32_bf16 v[114:117], v[186:189], v[202:205], v[114:117]
	v_mfma_f32_16x16x32_bf16 v[110:113], v[174:177], v[206:209], v[110:113]
	v_mfma_f32_16x16x32_bf16 v[110:113], v[178:181], v[210:213], v[110:113]
	v_mfma_f32_16x16x32_bf16 v[106:109], v[182:185], v[206:209], v[106:109]
	v_mfma_f32_16x16x32_bf16 v[106:109], v[186:189], v[210:213], v[106:109]
	v_mfma_f32_16x16x32_bf16 v[102:105], v[174:177], v[214:217], v[102:105]
	v_mfma_f32_16x16x32_bf16 v[102:105], v[178:181], v[218:221], v[102:105]
	v_mfma_f32_16x16x32_bf16 v[98:101], v[182:185], v[214:217], v[98:101]
	v_mfma_f32_16x16x32_bf16 v[98:101], v[186:189], v[218:221], v[98:101]
	s_barrier
	s_add_u32 s36, s34, 0x4000
	s_addc_u32 s37, s35, 0
	s_add_i32 s81, s81, s38
	s_mov_b32 m0, s81
	ds_read_b128 v[190:193], v161 offset:49152
	ds_read_b128 v[194:197], v161 offset:50176
	ds_read_b128 v[198:201], v161 offset:51200
	ds_read_b128 v[202:205], v161 offset:52224
	ds_read_b128 v[206:209], v161 offset:53248
	ds_read_b128 v[210:213], v161 offset:54272
	ds_read_b128 v[214:217], v161 offset:55296
	ds_read_b128 v[218:221], v161 offset:56320
	global_load_lds_dwordx4 v138, s[36:37]
	s_add_i32 m0, s81, 0x2000
	s_add_u32 s34, s34, 0x104000
	s_addc_u32 s35, s35, 0
	global_load_lds_dwordx4 v134, s[36:37]
	s_add_i32 s36, s83, s38
	s_mov_b32 m0, s36
	s_nop 0
	global_load_lds_dwordx4 v138, s[34:35]
	s_add_i32 m0, s36, 0x2000
	s_nop 0
	global_load_lds_dwordx4 v134, s[34:35]
	s_mov_b32 m0, s58
	s_nop 0
	global_load_lds_dwordx4 v140, s[30:31]
	s_mov_b32 m0, s59
	s_nop 0
	global_load_lds_dwordx4 v136, s[30:31]
	s_waitcnt vmcnt(8) lgkmcnt(0)
	s_barrier
	v_mfma_f32_16x16x32_bf16 v[30:33], v[130:133], v[190:193], v[30:33]
	v_mfma_f32_16x16x32_bf16 v[30:33], v[162:165], v[194:197], v[30:33]
	v_mfma_f32_16x16x32_bf16 v[26:29], v[166:169], v[190:193], v[26:29]
	v_mfma_f32_16x16x32_bf16 v[26:29], v[170:173], v[194:197], v[26:29]
	v_mfma_f32_16x16x32_bf16 v[22:25], v[130:133], v[198:201], v[22:25]
	v_mfma_f32_16x16x32_bf16 v[22:25], v[162:165], v[202:205], v[22:25]
	v_mfma_f32_16x16x32_bf16 v[18:21], v[166:169], v[198:201], v[18:21]
	v_mfma_f32_16x16x32_bf16 v[18:21], v[170:173], v[202:205], v[18:21]
	v_mfma_f32_16x16x32_bf16 v[14:17], v[130:133], v[206:209], v[14:17]
	v_mfma_f32_16x16x32_bf16 v[14:17], v[162:165], v[210:213], v[14:17]
	v_mfma_f32_16x16x32_bf16 v[10:13], v[166:169], v[206:209], v[10:13]
	v_mfma_f32_16x16x32_bf16 v[10:13], v[170:173], v[210:213], v[10:13]
	v_mfma_f32_16x16x32_bf16 v[6:9], v[130:133], v[214:217], v[6:9]
	v_mfma_f32_16x16x32_bf16 v[6:9], v[162:165], v[218:221], v[6:9]
	v_mfma_f32_16x16x32_bf16 v[2:5], v[166:169], v[214:217], v[2:5]
	v_mfma_f32_16x16x32_bf16 v[2:5], v[170:173], v[218:221], v[2:5]
	v_mfma_f32_16x16x32_bf16 v[94:97], v[174:177], v[190:193], v[94:97]
	v_mfma_f32_16x16x32_bf16 v[94:97], v[178:181], v[194:197], v[94:97]
	v_mfma_f32_16x16x32_bf16 v[90:93], v[182:185], v[190:193], v[90:93]
	v_mfma_f32_16x16x32_bf16 v[90:93], v[186:189], v[194:197], v[90:93]
	v_mfma_f32_16x16x32_bf16 v[86:89], v[174:177], v[198:201], v[86:89]
	v_mfma_f32_16x16x32_bf16 v[86:89], v[178:181], v[202:205], v[86:89]
	v_mfma_f32_16x16x32_bf16 v[82:85], v[182:185], v[198:201], v[82:85]
	v_mfma_f32_16x16x32_bf16 v[82:85], v[186:189], v[202:205], v[82:85]
	v_mfma_f32_16x16x32_bf16 v[78:81], v[174:177], v[206:209], v[78:81]
	v_mfma_f32_16x16x32_bf16 v[78:81], v[178:181], v[210:213], v[78:81]
	v_mfma_f32_16x16x32_bf16 v[74:77], v[182:185], v[206:209], v[74:77]
	v_mfma_f32_16x16x32_bf16 v[74:77], v[186:189], v[210:213], v[74:77]
	v_mfma_f32_16x16x32_bf16 v[70:73], v[174:177], v[214:217], v[70:73]
	v_mfma_f32_16x16x32_bf16 v[70:73], v[178:181], v[218:221], v[70:73]
	v_mfma_f32_16x16x32_bf16 v[66:69], v[182:185], v[214:217], v[66:69]
	v_mfma_f32_16x16x32_bf16 v[66:69], v[186:189], v[218:221], v[66:69]
	s_barrier
	s_add_i32 s80, s80, 2
	s_add_u32 s26, s26, 0x8000
	s_addc_u32 s27, s27, 0
	s_add_u32 s78, s78, 0x8000
	s_addc_u32 s79, s79, 0
	s_cmp_gt_u32 s80, 61
	s_cbranch_scc0 .LBB0_536
	s_and_b64 vcc, exec, s[14:15]
	s_cbranch_vccz .LBB0_539
	s_barrier

.LBB0_1005:
	v_add_u32_e32 v142, s46, v200
	v_add_u32_e32 v158, s47, v200
	ds_read_b128 v[130:133], v142
	ds_read_b128 v[134:137], v142 offset:1024
	ds_read_b128 v[138:141], v142 offset:2048
	ds_read_b128 v[142:145], v142 offset:3072
	ds_read_b128 v[146:149], v158
	ds_read_b128 v[150:153], v158 offset:1024
	ds_read_b128 v[154:157], v158 offset:2048
	ds_read_b128 v[158:161], v158 offset:3072
	s_add_i32 s70, s31, 2
	s_add_u32 s26, s24, 0xfff44000
	s_addc_u32 s27, s25, -1
	s_cmp_eq_u32 s67, s31
	s_cselect_b32 s34, s6, s26
	s_cselect_b32 s35, s7, s27
	s_cselect_b32 s30, s20, s68
	s_cselect_b32 s31, s21, s69
	s_add_u32 s26, s34, 0x4000
	s_addc_u32 s27, s35, 0
	s_add_i32 m0, s37, 0xc000
	ds_read_b128 v[162:165], v201
	ds_read_b128 v[166:169], v201 offset:1024
	ds_read_b128 v[170:173], v201 offset:2048
	ds_read_b128 v[174:177], v201 offset:3072
	ds_read_b128 v[202:205], v201 offset:4096
	ds_read_b128 v[206:209], v201 offset:5120
	ds_read_b128 v[210:213], v201 offset:6144
	ds_read_b128 v[214:217], v201 offset:7168
	global_load_lds_dwordx4 v190, s[24:25]
	s_add_i32 m0, s37, 0xe000
	s_nop 0
	global_load_lds_dwordx4 v192, s[24:25]
	s_waitcnt vmcnt(8) lgkmcnt(0)
	s_barrier
	v_mfma_f32_16x16x32_bf16 v[126:129], v[130:133], v[162:165], v[126:129]
	v_mfma_f32_16x16x32_bf16 v[126:129], v[134:137], v[166:169], v[126:129]
	v_mfma_f32_16x16x32_bf16 v[122:125], v[138:141], v[162:165], v[122:125]
	v_mfma_f32_16x16x32_bf16 v[122:125], v[142:145], v[166:169], v[122:125]
	v_mfma_f32_16x16x32_bf16 v[118:121], v[130:133], v[170:173], v[118:121]
	v_mfma_f32_16x16x32_bf16 v[118:121], v[134:137], v[174:177], v[118:121]
	v_mfma_f32_16x16x32_bf16 v[114:117], v[138:141], v[170:173], v[114:117]
	v_mfma_f32_16x16x32_bf16 v[114:117], v[142:145], v[174:177], v[114:117]
	v_mfma_f32_16x16x32_bf16 v[110:113], v[130:133], v[202:205], v[110:113]
	v_mfma_f32_16x16x32_bf16 v[110:113], v[134:137], v[206:209], v[110:113]
	v_mfma_f32_16x16x32_bf16 v[106:109], v[138:141], v[202:205], v[106:109]
	v_mfma_f32_16x16x32_bf16 v[106:109], v[142:145], v[206:209], v[106:109]
	v_mfma_f32_16x16x32_bf16 v[102:105], v[130:133], v[210:213], v[102:105]
	v_mfma_f32_16x16x32_bf16 v[102:105], v[134:137], v[214:217], v[102:105]
	v_mfma_f32_16x16x32_bf16 v[98:101], v[138:141], v[210:213], v[98:101]
	v_mfma_f32_16x16x32_bf16 v[98:101], v[142:145], v[214:217], v[98:101]
	v_mfma_f32_16x16x32_bf16 v[94:97], v[146:149], v[162:165], v[94:97]
	v_mfma_f32_16x16x32_bf16 v[94:97], v[150:153], v[166:169], v[94:97]
	v_mfma_f32_16x16x32_bf16 v[90:93], v[154:157], v[162:165], v[90:93]
	v_mfma_f32_16x16x32_bf16 v[90:93], v[158:161], v[166:169], v[90:93]
	v_mfma_f32_16x16x32_bf16 v[86:89], v[146:149], v[170:173], v[86:89]
	v_mfma_f32_16x16x32_bf16 v[86:89], v[150:153], v[174:177], v[86:89]
	v_mfma_f32_16x16x32_bf16 v[82:85], v[154:157], v[170:173], v[82:85]
	v_mfma_f32_16x16x32_bf16 v[82:85], v[158:161], v[174:177], v[82:85]
	v_mfma_f32_16x16x32_bf16 v[78:81], v[146:149], v[202:205], v[78:81]
	v_mfma_f32_16x16x32_bf16 v[78:81], v[150:153], v[206:209], v[78:81]
	v_mfma_f32_16x16x32_bf16 v[74:77], v[154:157], v[202:205], v[74:77]
	v_mfma_f32_16x16x32_bf16 v[74:77], v[158:161], v[206:209], v[74:77]
	v_mfma_f32_16x16x32_bf16 v[66:69], v[146:149], v[210:213], v[66:69]
	v_mfma_f32_16x16x32_bf16 v[66:69], v[150:153], v[214:217], v[66:69]
	v_mfma_f32_16x16x32_bf16 v[58:61], v[154:157], v[210:213], v[58:61]
	v_mfma_f32_16x16x32_bf16 v[58:61], v[158:161], v[214:217], v[58:61]
	s_barrier
	s_add_i32 s71, s46, s36
	s_mov_b32 m0, s71
	ds_read_b128 v[162:165], v201 offset:16384
	ds_read_b128 v[166:169], v201 offset:17408
	ds_read_b128 v[170:173], v201 offset:18432
	ds_read_b128 v[174:177], v201 offset:19456
	ds_read_b128 v[202:205], v201 offset:20480
	ds_read_b128 v[206:209], v201 offset:21504
	ds_read_b128 v[210:213], v201 offset:22528
	ds_read_b128 v[214:217], v201 offset:23552
	global_load_lds_dwordx4 v182, s[30:31]
	s_add_i32 m0, s71, 0x2000
	s_add_u32 s72, s30, 0xc0000
	s_addc_u32 s73, s31, 0
	s_add_i32 s71, s47, s36
	global_load_lds_dwordx4 v178, s[30:31]
	s_mov_b32 m0, s71
	s_nop 0
	global_load_lds_dwordx4 v182, s[72:73]
	s_add_i32 m0, s71, 0x2000
	s_nop 0
	global_load_lds_dwordx4 v178, s[72:73]
	s_mov_b32 m0, s37
	s_nop 0
	global_load_lds_dwordx4 v184, s[34:35]
	s_mov_b32 m0, s38
	s_nop 0
	global_load_lds_dwordx4 v180, s[34:35]
	s_waitcnt vmcnt(8) lgkmcnt(0)
	s_barrier
	v_mfma_f32_16x16x32_bf16 v[70:73], v[130:133], v[162:165], v[70:73]
	v_mfma_f32_16x16x32_bf16 v[70:73], v[134:137], v[166:169], v[70:73]
	v_mfma_f32_16x16x32_bf16 v[62:65], v[138:141], v[162:165], v[62:65]
	v_mfma_f32_16x16x32_bf16 v[62:65], v[142:145], v[166:169], v[62:65]
	v_mfma_f32_16x16x32_bf16 v[54:57], v[130:133], v[170:173], v[54:57]
	v_mfma_f32_16x16x32_bf16 v[54:57], v[134:137], v[174:177], v[54:57]
	v_mfma_f32_16x16x32_bf16 v[50:53], v[138:141], v[170:173], v[50:53]
	v_mfma_f32_16x16x32_bf16 v[50:53], v[142:145], v[174:177], v[50:53]
	v_mfma_f32_16x16x32_bf16 v[46:49], v[130:133], v[202:205], v[46:49]
	v_mfma_f32_16x16x32_bf16 v[46:49], v[134:137], v[206:209], v[46:49]
	v_mfma_f32_16x16x32_bf16 v[42:45], v[138:141], v[202:205], v[42:45]
	v_mfma_f32_16x16x32_bf16 v[42:45], v[142:145], v[206:209], v[42:45]
	v_mfma_f32_16x16x32_bf16 v[38:41], v[130:133], v[210:213], v[38:41]
	v_mfma_f32_16x16x32_bf16 v[38:41], v[134:137], v[214:217], v[38:41]
	v_mfma_f32_16x16x32_bf16 v[34:37], v[138:141], v[210:213], v[34:37]
	v_mfma_f32_16x16x32_bf16 v[34:37], v[142:145], v[214:217], v[34:37]
	v_mfma_f32_16x16x32_bf16 v[30:33], v[146:149], v[162:165], v[30:33]
	v_mfma_f32_16x16x32_bf16 v[30:33], v[150:153], v[166:169], v[30:33]
	v_mfma_f32_16x16x32_bf16 v[26:29], v[154:157], v[162:165], v[26:29]
	v_mfma_f32_16x16x32_bf16 v[26:29], v[158:161], v[166:169], v[26:29]
	v_mfma_f32_16x16x32_bf16 v[22:25], v[146:149], v[170:173], v[22:25]
	v_mfma_f32_16x16x32_bf16 v[22:25], v[150:153], v[174:177], v[22:25]
	v_mfma_f32_16x16x32_bf16 v[18:21], v[154:157], v[170:173], v[18:21]
	v_mfma_f32_16x16x32_bf16 v[18:21], v[158:161], v[174:177], v[18:21]
	v_mfma_f32_16x16x32_bf16 v[14:17], v[146:149], v[202:205], v[14:17]
	v_mfma_f32_16x16x32_bf16 v[14:17], v[150:153], v[206:209], v[14:17]
	v_mfma_f32_16x16x32_bf16 v[10:13], v[154:157], v[202:205], v[10:13]
	v_mfma_f32_16x16x32_bf16 v[10:13], v[158:161], v[206:209], v[10:13]
	v_mfma_f32_16x16x32_bf16 v[6:9], v[146:149], v[210:213], v[6:9]
	v_mfma_f32_16x16x32_bf16 v[6:9], v[150:153], v[214:217], v[6:9]
	v_mfma_f32_16x16x32_bf16 v[2:5], v[154:157], v[210:213], v[2:5]
	v_mfma_f32_16x16x32_bf16 v[2:5], v[158:161], v[214:217], v[2:5]
	s_barrier
	s_add_i32 s71, 0, 0x18000
	s_add_i32 s72, 0, 0x1c000
	v_add_u32_e32 v142, s71, v200
	v_add_u32_e32 v158, s72, v200
	ds_read_b128 v[130:133], v142
	ds_read_b128 v[134:137], v142 offset:1024
	ds_read_b128 v[138:141], v142 offset:2048
	ds_read_b128 v[142:145], v142 offset:3072
	ds_read_b128 v[146:149], v158
	ds_read_b128 v[150:153], v158 offset:1024
	ds_read_b128 v[154:157], v158 offset:2048
	ds_read_b128 v[158:161], v158 offset:3072
	s_add_u32 s34, s34, 0xc0000
	s_addc_u32 s35, s35, 0
	s_mov_b32 m0, s39
	ds_read_b128 v[162:165], v201 offset:32768
	ds_read_b128 v[166:169], v201 offset:33792
	ds_read_b128 v[170:173], v201 offset:34816
	ds_read_b128 v[174:177], v201 offset:35840
	ds_read_b128 v[202:205], v201 offset:36864
	ds_read_b128 v[206:209], v201 offset:37888
	ds_read_b128 v[210:213], v201 offset:38912
	ds_read_b128 v[214:217], v201 offset:39936
	global_load_lds_dwordx4 v184, s[34:35]
	s_mov_b32 m0, s40
	s_nop 0
	global_load_lds_dwordx4 v180, s[34:35]
	s_waitcnt vmcnt(8) lgkmcnt(0)
	s_barrier
	v_mfma_f32_16x16x32_bf16 v[126:129], v[130:133], v[162:165], v[126:129]
	v_mfma_f32_16x16x32_bf16 v[126:129], v[134:137], v[166:169], v[126:129]
	v_mfma_f32_16x16x32_bf16 v[122:125], v[138:141], v[162:165], v[122:125]
	v_mfma_f32_16x16x32_bf16 v[122:125], v[142:145], v[166:169], v[122:125]
	v_mfma_f32_16x16x32_bf16 v[118:121], v[130:133], v[170:173], v[118:121]
	v_mfma_f32_16x16x32_bf16 v[118:121], v[134:137], v[174:177], v[118:121]
	v_mfma_f32_16x16x32_bf16 v[114:117], v[138:141], v[170:173], v[114:117]
	v_mfma_f32_16x16x32_bf16 v[114:117], v[142:145], v[174:177], v[114:117]
	v_mfma_f32_16x16x32_bf16 v[110:113], v[130:133], v[202:205], v[110:113]
	v_mfma_f32_16x16x32_bf16 v[110:113], v[134:137], v[206:209], v[110:113]
	v_mfma_f32_16x16x32_bf16 v[106:109], v[138:141], v[202:205], v[106:109]
	v_mfma_f32_16x16x32_bf16 v[106:109], v[142:145], v[206:209], v[106:109]
	v_mfma_f32_16x16x32_bf16 v[102:105], v[130:133], v[210:213], v[102:105]
	v_mfma_f32_16x16x32_bf16 v[102:105], v[134:137], v[214:217], v[102:105]
	v_mfma_f32_16x16x32_bf16 v[98:101], v[138:141], v[210:213], v[98:101]
	v_mfma_f32_16x16x32_bf16 v[98:101], v[142:145], v[214:217], v[98:101]
	v_mfma_f32_16x16x32_bf16 v[94:97], v[146:149], v[162:165], v[94:97]
	v_mfma_f32_16x16x32_bf16 v[94:97], v[150:153], v[166:169], v[94:97]
	v_mfma_f32_16x16x32_bf16 v[90:93], v[154:157], v[162:165], v[90:93]
	v_mfma_f32_16x16x32_bf16 v[90:93], v[158:161], v[166:169], v[90:93]
	v_mfma_f32_16x16x32_bf16 v[86:89], v[146:149], v[170:173], v[86:89]
	v_mfma_f32_16x16x32_bf16 v[86:89], v[150:153], v[174:177], v[86:89]
	v_mfma_f32_16x16x32_bf16 v[82:85], v[154:157], v[170:173], v[82:85]
	v_mfma_f32_16x16x32_bf16 v[82:85], v[158:161], v[174:177], v[82:85]
	v_mfma_f32_16x16x32_bf16 v[78:81], v[146:149], v[202:205], v[78:81]
	v_mfma_f32_16x16x32_bf16 v[78:81], v[150:153], v[206:209], v[78:81]
	v_mfma_f32_16x16x32_bf16 v[74:77], v[154:157], v[202:205], v[74:77]
	v_mfma_f32_16x16x32_bf16 v[74:77], v[158:161], v[206:209], v[74:77]
	v_mfma_f32_16x16x32_bf16 v[66:69], v[146:149], v[210:213], v[66:69]
	v_mfma_f32_16x16x32_bf16 v[66:69], v[150:153], v[214:217], v[66:69]
	v_mfma_f32_16x16x32_bf16 v[58:61], v[154:157], v[210:213], v[58:61]
	v_mfma_f32_16x16x32_bf16 v[58:61], v[158:161], v[214:217], v[58:61]
	s_barrier
	s_add_u32 s34, s30, 0x4000
	s_addc_u32 s35, s31, 0
	s_add_i32 s71, s71, s36
	s_mov_b32 m0, s71
	ds_read_b128 v[162:165], v201 offset:49152
	ds_read_b128 v[166:169], v201 offset:50176
	ds_read_b128 v[170:173], v201 offset:51200
	ds_read_b128 v[174:177], v201 offset:52224
	ds_read_b128 v[202:205], v201 offset:53248
	ds_read_b128 v[206:209], v201 offset:54272
	ds_read_b128 v[210:213], v201 offset:55296
	ds_read_b128 v[214:217], v201 offset:56320
	global_load_lds_dwordx4 v182, s[34:35]
	s_add_i32 m0, s71, 0x2000
	s_add_u32 s30, s30, 0xc4000
	s_addc_u32 s31, s31, 0
	global_load_lds_dwordx4 v178, s[34:35]
	s_add_i32 s34, s72, s36
	s_mov_b32 m0, s34
	s_nop 0
	global_load_lds_dwordx4 v182, s[30:31]
	s_add_i32 m0, s34, 0x2000
	s_nop 0
	global_load_lds_dwordx4 v178, s[30:31]
	s_mov_b32 m0, s42
	s_nop 0
	global_load_lds_dwordx4 v184, s[26:27]
	s_mov_b32 m0, s43
	s_nop 0
	global_load_lds_dwordx4 v180, s[26:27]
	s_waitcnt vmcnt(8) lgkmcnt(0)
	s_barrier
	v_mfma_f32_16x16x32_bf16 v[70:73], v[130:133], v[162:165], v[70:73]
	v_mfma_f32_16x16x32_bf16 v[70:73], v[134:137], v[166:169], v[70:73]
	v_mfma_f32_16x16x32_bf16 v[62:65], v[138:141], v[162:165], v[62:65]
	v_mfma_f32_16x16x32_bf16 v[62:65], v[142:145], v[166:169], v[62:65]
	v_mfma_f32_16x16x32_bf16 v[54:57], v[130:133], v[170:173], v[54:57]
	v_mfma_f32_16x16x32_bf16 v[54:57], v[134:137], v[174:177], v[54:57]
	v_mfma_f32_16x16x32_bf16 v[50:53], v[138:141], v[170:173], v[50:53]
	v_mfma_f32_16x16x32_bf16 v[50:53], v[142:145], v[174:177], v[50:53]
	v_mfma_f32_16x16x32_bf16 v[46:49], v[130:133], v[202:205], v[46:49]
	v_mfma_f32_16x16x32_bf16 v[46:49], v[134:137], v[206:209], v[46:49]
	v_mfma_f32_16x16x32_bf16 v[42:45], v[138:141], v[202:205], v[42:45]
	v_mfma_f32_16x16x32_bf16 v[42:45], v[142:145], v[206:209], v[42:45]
	v_mfma_f32_16x16x32_bf16 v[38:41], v[130:133], v[210:213], v[38:41]
	v_mfma_f32_16x16x32_bf16 v[38:41], v[134:137], v[214:217], v[38:41]
	v_mfma_f32_16x16x32_bf16 v[34:37], v[138:141], v[210:213], v[34:37]
	v_mfma_f32_16x16x32_bf16 v[34:37], v[142:145], v[214:217], v[34:37]
	v_mfma_f32_16x16x32_bf16 v[30:33], v[146:149], v[162:165], v[30:33]
	v_mfma_f32_16x16x32_bf16 v[30:33], v[150:153], v[166:169], v[30:33]
	v_mfma_f32_16x16x32_bf16 v[26:29], v[154:157], v[162:165], v[26:29]
	v_mfma_f32_16x16x32_bf16 v[26:29], v[158:161], v[166:169], v[26:29]
	v_mfma_f32_16x16x32_bf16 v[22:25], v[146:149], v[170:173], v[22:25]
	v_mfma_f32_16x16x32_bf16 v[22:25], v[150:153], v[174:177], v[22:25]
	v_mfma_f32_16x16x32_bf16 v[18:21], v[154:157], v[170:173], v[18:21]
	v_mfma_f32_16x16x32_bf16 v[18:21], v[158:161], v[174:177], v[18:21]
	v_mfma_f32_16x16x32_bf16 v[14:17], v[146:149], v[202:205], v[14:17]
	v_mfma_f32_16x16x32_bf16 v[14:17], v[150:153], v[206:209], v[14:17]
	v_mfma_f32_16x16x32_bf16 v[10:13], v[154:157], v[202:205], v[10:13]
	v_mfma_f32_16x16x32_bf16 v[10:13], v[158:161], v[206:209], v[10:13]
	v_mfma_f32_16x16x32_bf16 v[6:9], v[146:149], v[210:213], v[6:9]
	v_mfma_f32_16x16x32_bf16 v[6:9], v[150:153], v[214:217], v[6:9]
	v_mfma_f32_16x16x32_bf16 v[2:5], v[154:157], v[210:213], v[2:5]
	v_mfma_f32_16x16x32_bf16 v[2:5], v[158:161], v[214:217], v[2:5]
	s_barrier
	s_add_u32 s24, s24, 0x8000
	s_addc_u32 s25, s25, 0
	s_add_u32 s68, s68, 0x8000
	s_addc_u32 s69, s69, 0
	s_cmp_ge_u32 s70, s66
	s_mov_b32 s31, s70
	s_cbranch_scc0 .LBB0_1005
	s_and_b64 vcc, exec, s[18:19]
	s_cbranch_vccnz .LBB0_1010
	v_lshl_add_u32 v162, s65, 8, v189
	s_mov_b64 s[24:25], -1
	s_and_b64 vcc, exec, s[22:23]
	s_cbranch_vccnz .LBB0_1011

.LBB0_1088:
	ds_read_b128 v[130:133], v209
	ds_read_b128 v[134:137], v209 offset:1024
	ds_read_b128 v[138:141], v209 offset:2048
	ds_read_b128 v[142:145], v209 offset:3072
	ds_read_b128 v[146:149], v210
	ds_read_b128 v[150:153], v210 offset:1024
	ds_read_b128 v[154:157], v210 offset:2048
	ds_read_b128 v[158:161], v210 offset:3072
	s_add_u32 s38, s36, 0xfff04000
	s_addc_u32 s39, s37, -1
	s_cmp_eq_u32 s72, 60
	s_cselect_b32 s42, s35, s38
	s_cselect_b32 s43, s25, s39
	s_cselect_b32 s40, s69, s70
	s_cselect_b32 s41, s23, s71
	s_add_u32 s38, s42, 0x4000
	s_addc_u32 s39, s43, 0
	s_add_i32 m0, s47, 0xc000
	ds_read_b128 v[162:165], v211
	ds_read_b128 v[166:169], v211 offset:1024
	ds_read_b128 v[170:173], v211 offset:2048
	ds_read_b128 v[174:177], v211 offset:3072
	ds_read_b128 v[196:199], v211 offset:4096
	ds_read_b128 v[200:203], v211 offset:5120
	ds_read_b128 v[214:217], v211 offset:6144
	ds_read_b128 v[218:221], v211 offset:7168
	global_load_lds_dwordx4 v188, s[36:37]
	s_add_i32 m0, s47, 0xe000
	s_nop 0
	global_load_lds_dwordx4 v190, s[36:37]
	s_waitcnt vmcnt(8) lgkmcnt(0)
	s_barrier
	v_mfma_f32_16x16x32_bf16 v[126:129], v[130:133], v[162:165], v[126:129]
	v_mfma_f32_16x16x32_bf16 v[126:129], v[134:137], v[166:169], v[126:129]
	v_mfma_f32_16x16x32_bf16 v[122:125], v[138:141], v[162:165], v[122:125]
	v_mfma_f32_16x16x32_bf16 v[122:125], v[142:145], v[166:169], v[122:125]
	v_mfma_f32_16x16x32_bf16 v[110:113], v[130:133], v[170:173], v[110:113]
	v_mfma_f32_16x16x32_bf16 v[110:113], v[134:137], v[174:177], v[110:113]
	v_mfma_f32_16x16x32_bf16 v[106:109], v[138:141], v[170:173], v[106:109]
	v_mfma_f32_16x16x32_bf16 v[106:109], v[142:145], v[174:177], v[106:109]
	v_mfma_f32_16x16x32_bf16 v[94:97], v[130:133], v[196:199], v[94:97]
	v_mfma_f32_16x16x32_bf16 v[94:97], v[134:137], v[200:203], v[94:97]
	v_mfma_f32_16x16x32_bf16 v[90:93], v[138:141], v[196:199], v[90:93]
	v_mfma_f32_16x16x32_bf16 v[90:93], v[142:145], v[200:203], v[90:93]
	v_mfma_f32_16x16x32_bf16 v[78:81], v[130:133], v[214:217], v[78:81]
	v_mfma_f32_16x16x32_bf16 v[78:81], v[134:137], v[218:221], v[78:81]
	v_mfma_f32_16x16x32_bf16 v[74:77], v[138:141], v[214:217], v[74:77]
	v_mfma_f32_16x16x32_bf16 v[74:77], v[142:145], v[218:221], v[74:77]
	v_mfma_f32_16x16x32_bf16 v[118:121], v[146:149], v[162:165], v[118:121]
	v_mfma_f32_16x16x32_bf16 v[118:121], v[150:153], v[166:169], v[118:121]
	v_mfma_f32_16x16x32_bf16 v[114:117], v[154:157], v[162:165], v[114:117]
	v_mfma_f32_16x16x32_bf16 v[114:117], v[158:161], v[166:169], v[114:117]
	v_mfma_f32_16x16x32_bf16 v[102:105], v[146:149], v[170:173], v[102:105]
	v_mfma_f32_16x16x32_bf16 v[102:105], v[150:153], v[174:177], v[102:105]
	v_mfma_f32_16x16x32_bf16 v[98:101], v[154:157], v[170:173], v[98:101]
	v_mfma_f32_16x16x32_bf16 v[98:101], v[158:161], v[174:177], v[98:101]
	v_mfma_f32_16x16x32_bf16 v[86:89], v[146:149], v[196:199], v[86:89]
	v_mfma_f32_16x16x32_bf16 v[86:89], v[150:153], v[200:203], v[86:89]
	v_mfma_f32_16x16x32_bf16 v[82:85], v[154:157], v[196:199], v[82:85]
	v_mfma_f32_16x16x32_bf16 v[82:85], v[158:161], v[200:203], v[82:85]
	v_mfma_f32_16x16x32_bf16 v[70:73], v[146:149], v[214:217], v[70:73]
	v_mfma_f32_16x16x32_bf16 v[70:73], v[150:153], v[218:221], v[70:73]
	v_mfma_f32_16x16x32_bf16 v[66:69], v[154:157], v[214:217], v[66:69]
	v_mfma_f32_16x16x32_bf16 v[66:69], v[158:161], v[218:221], v[66:69]
	s_barrier
	s_add_i32 s73, s66, s46
	s_mov_b32 m0, s73
	ds_read_b128 v[162:165], v211 offset:16384
	ds_read_b128 v[166:169], v211 offset:17408
	ds_read_b128 v[170:173], v211 offset:18432
	ds_read_b128 v[174:177], v211 offset:19456
	ds_read_b128 v[196:199], v211 offset:20480
	ds_read_b128 v[200:203], v211 offset:21504
	ds_read_b128 v[214:217], v211 offset:22528
	ds_read_b128 v[218:221], v211 offset:23552
	global_load_lds_dwordx4 v180, s[40:41]
	s_add_i32 m0, s73, 0x2000
	s_add_u32 s74, s40, 0x100000
	s_addc_u32 s75, s41, 0
	s_add_i32 s73, s67, s46
	global_load_lds_dwordx4 v184, s[40:41]
	s_mov_b32 m0, s73
	s_nop 0
	global_load_lds_dwordx4 v180, s[74:75]
	s_add_i32 m0, s73, 0x2000
	s_nop 0
	global_load_lds_dwordx4 v184, s[74:75]
	s_mov_b32 m0, s47
	s_nop 0
	global_load_lds_dwordx4 v178, s[42:43]
	s_mov_b32 m0, s59
	s_nop 0
	global_load_lds_dwordx4 v182, s[42:43]
	s_waitcnt vmcnt(8) lgkmcnt(0)
	s_barrier
	v_mfma_f32_16x16x32_bf16 v[62:65], v[130:133], v[162:165], v[62:65]
	v_mfma_f32_16x16x32_bf16 v[62:65], v[134:137], v[166:169], v[62:65]
	v_mfma_f32_16x16x32_bf16 v[58:61], v[138:141], v[162:165], v[58:61]
	v_mfma_f32_16x16x32_bf16 v[58:61], v[142:145], v[166:169], v[58:61]
	v_mfma_f32_16x16x32_bf16 v[46:49], v[130:133], v[170:173], v[46:49]
	v_mfma_f32_16x16x32_bf16 v[46:49], v[134:137], v[174:177], v[46:49]
	v_mfma_f32_16x16x32_bf16 v[42:45], v[138:141], v[170:173], v[42:45]
	v_mfma_f32_16x16x32_bf16 v[42:45], v[142:145], v[174:177], v[42:45]
	v_mfma_f32_16x16x32_bf16 v[30:33], v[130:133], v[196:199], v[30:33]
	v_mfma_f32_16x16x32_bf16 v[30:33], v[134:137], v[200:203], v[30:33]
	v_mfma_f32_16x16x32_bf16 v[26:29], v[138:141], v[196:199], v[26:29]
	v_mfma_f32_16x16x32_bf16 v[26:29], v[142:145], v[200:203], v[26:29]
	v_mfma_f32_16x16x32_bf16 v[14:17], v[130:133], v[214:217], v[14:17]
	v_mfma_f32_16x16x32_bf16 v[14:17], v[134:137], v[218:221], v[14:17]
	v_mfma_f32_16x16x32_bf16 v[10:13], v[138:141], v[214:217], v[10:13]
	v_mfma_f32_16x16x32_bf16 v[10:13], v[142:145], v[218:221], v[10:13]
	v_mfma_f32_16x16x32_bf16 v[54:57], v[146:149], v[162:165], v[54:57]
	v_mfma_f32_16x16x32_bf16 v[54:57], v[150:153], v[166:169], v[54:57]
	v_mfma_f32_16x16x32_bf16 v[50:53], v[154:157], v[162:165], v[50:53]
	v_mfma_f32_16x16x32_bf16 v[50:53], v[158:161], v[166:169], v[50:53]
	v_mfma_f32_16x16x32_bf16 v[38:41], v[146:149], v[170:173], v[38:41]
	v_mfma_f32_16x16x32_bf16 v[38:41], v[150:153], v[174:177], v[38:41]
	v_mfma_f32_16x16x32_bf16 v[34:37], v[154:157], v[170:173], v[34:37]
	v_mfma_f32_16x16x32_bf16 v[34:37], v[158:161], v[174:177], v[34:37]
	v_mfma_f32_16x16x32_bf16 v[22:25], v[146:149], v[196:199], v[22:25]
	v_mfma_f32_16x16x32_bf16 v[22:25], v[150:153], v[200:203], v[22:25]
	v_mfma_f32_16x16x32_bf16 v[18:21], v[154:157], v[196:199], v[18:21]
	v_mfma_f32_16x16x32_bf16 v[18:21], v[158:161], v[200:203], v[18:21]
	v_mfma_f32_16x16x32_bf16 v[6:9], v[146:149], v[214:217], v[6:9]
	v_mfma_f32_16x16x32_bf16 v[6:9], v[150:153], v[218:221], v[6:9]
	v_mfma_f32_16x16x32_bf16 v[2:5], v[154:157], v[214:217], v[2:5]
	v_mfma_f32_16x16x32_bf16 v[2:5], v[158:161], v[218:221], v[2:5]
	s_barrier
	s_add_i32 s73, 0, 0x18000
	s_add_i32 s74, 0, 0x1c000
	v_add_u32_e32 v142, s73, v208
	v_add_u32_e32 v158, s74, v208
	ds_read_b128 v[130:133], v142
	ds_read_b128 v[134:137], v142 offset:1024
	ds_read_b128 v[138:141], v142 offset:2048
	ds_read_b128 v[142:145], v142 offset:3072
	ds_read_b128 v[146:149], v158
	ds_read_b128 v[150:153], v158 offset:1024
	ds_read_b128 v[154:157], v158 offset:2048
	ds_read_b128 v[158:161], v158 offset:3072
	s_add_u32 s42, s42, 0x100000
	s_addc_u32 s43, s43, 0
	s_mov_b32 m0, s60
	ds_read_b128 v[162:165], v211 offset:32768
	ds_read_b128 v[166:169], v211 offset:33792
	ds_read_b128 v[170:173], v211 offset:34816
	ds_read_b128 v[174:177], v211 offset:35840
	ds_read_b128 v[196:199], v211 offset:36864
	ds_read_b128 v[200:203], v211 offset:37888
	ds_read_b128 v[214:217], v211 offset:38912
	ds_read_b128 v[218:221], v211 offset:39936
	global_load_lds_dwordx4 v178, s[42:43]
	s_mov_b32 m0, s61
	s_nop 0
	global_load_lds_dwordx4 v182, s[42:43]
	s_waitcnt vmcnt(8) lgkmcnt(0)
	s_barrier
	v_mfma_f32_16x16x32_bf16 v[126:129], v[130:133], v[162:165], v[126:129]
	v_mfma_f32_16x16x32_bf16 v[126:129], v[134:137], v[166:169], v[126:129]
	v_mfma_f32_16x16x32_bf16 v[122:125], v[138:141], v[162:165], v[122:125]
	v_mfma_f32_16x16x32_bf16 v[122:125], v[142:145], v[166:169], v[122:125]
	v_mfma_f32_16x16x32_bf16 v[110:113], v[130:133], v[170:173], v[110:113]
	v_mfma_f32_16x16x32_bf16 v[110:113], v[134:137], v[174:177], v[110:113]
	v_mfma_f32_16x16x32_bf16 v[106:109], v[138:141], v[170:173], v[106:109]
	v_mfma_f32_16x16x32_bf16 v[106:109], v[142:145], v[174:177], v[106:109]
	v_mfma_f32_16x16x32_bf16 v[94:97], v[130:133], v[196:199], v[94:97]
	v_mfma_f32_16x16x32_bf16 v[94:97], v[134:137], v[200:203], v[94:97]
	v_mfma_f32_16x16x32_bf16 v[90:93], v[138:141], v[196:199], v[90:93]
	v_mfma_f32_16x16x32_bf16 v[90:93], v[142:145], v[200:203], v[90:93]
	v_mfma_f32_16x16x32_bf16 v[78:81], v[130:133], v[214:217], v[78:81]
	v_mfma_f32_16x16x32_bf16 v[78:81], v[134:137], v[218:221], v[78:81]
	v_mfma_f32_16x16x32_bf16 v[74:77], v[138:141], v[214:217], v[74:77]
	v_mfma_f32_16x16x32_bf16 v[74:77], v[142:145], v[218:221], v[74:77]
	v_mfma_f32_16x16x32_bf16 v[118:121], v[146:149], v[162:165], v[118:121]
	v_mfma_f32_16x16x32_bf16 v[118:121], v[150:153], v[166:169], v[118:121]
	v_mfma_f32_16x16x32_bf16 v[114:117], v[154:157], v[162:165], v[114:117]
	v_mfma_f32_16x16x32_bf16 v[114:117], v[158:161], v[166:169], v[114:117]
	v_mfma_f32_16x16x32_bf16 v[102:105], v[146:149], v[170:173], v[102:105]
	v_mfma_f32_16x16x32_bf16 v[102:105], v[150:153], v[174:177], v[102:105]
	v_mfma_f32_16x16x32_bf16 v[98:101], v[154:157], v[170:173], v[98:101]
	v_mfma_f32_16x16x32_bf16 v[98:101], v[158:161], v[174:177], v[98:101]
	v_mfma_f32_16x16x32_bf16 v[86:89], v[146:149], v[196:199], v[86:89]
	v_mfma_f32_16x16x32_bf16 v[86:89], v[150:153], v[200:203], v[86:89]
	v_mfma_f32_16x16x32_bf16 v[82:85], v[154:157], v[196:199], v[82:85]
	v_mfma_f32_16x16x32_bf16 v[82:85], v[158:161], v[200:203], v[82:85]
	v_mfma_f32_16x16x32_bf16 v[70:73], v[146:149], v[214:217], v[70:73]
	v_mfma_f32_16x16x32_bf16 v[70:73], v[150:153], v[218:221], v[70:73]
	v_mfma_f32_16x16x32_bf16 v[66:69], v[154:157], v[214:217], v[66:69]
	v_mfma_f32_16x16x32_bf16 v[66:69], v[158:161], v[218:221], v[66:69]
	s_barrier
	s_add_u32 s42, s40, 0x4000
	s_addc_u32 s43, s41, 0
	s_add_i32 s73, s73, s46
	s_mov_b32 m0, s73
	ds_read_b128 v[162:165], v211 offset:49152
	ds_read_b128 v[166:169], v211 offset:50176
	ds_read_b128 v[170:173], v211 offset:51200
	ds_read_b128 v[174:177], v211 offset:52224
	ds_read_b128 v[196:199], v211 offset:53248
	ds_read_b128 v[200:203], v211 offset:54272
	ds_read_b128 v[214:217], v211 offset:55296
	ds_read_b128 v[218:221], v211 offset:56320
	global_load_lds_dwordx4 v180, s[42:43]
	s_add_i32 m0, s73, 0x2000
	s_add_u32 s40, s40, 0x104000
	s_addc_u32 s41, s41, 0
	global_load_lds_dwordx4 v184, s[42:43]
	s_add_i32 s42, s74, s46
	s_mov_b32 m0, s42
	s_nop 0
	global_load_lds_dwordx4 v180, s[40:41]
	s_add_i32 m0, s42, 0x2000
	s_nop 0
	global_load_lds_dwordx4 v184, s[40:41]
	s_mov_b32 m0, s64
	s_nop 0
	global_load_lds_dwordx4 v178, s[38:39]
	s_mov_b32 m0, s65
	s_nop 0
	global_load_lds_dwordx4 v182, s[38:39]
	s_waitcnt vmcnt(8) lgkmcnt(0)
	s_barrier
	v_mfma_f32_16x16x32_bf16 v[62:65], v[130:133], v[162:165], v[62:65]
	v_mfma_f32_16x16x32_bf16 v[62:65], v[134:137], v[166:169], v[62:65]
	v_mfma_f32_16x16x32_bf16 v[58:61], v[138:141], v[162:165], v[58:61]
	v_mfma_f32_16x16x32_bf16 v[58:61], v[142:145], v[166:169], v[58:61]
	v_mfma_f32_16x16x32_bf16 v[46:49], v[130:133], v[170:173], v[46:49]
	v_mfma_f32_16x16x32_bf16 v[46:49], v[134:137], v[174:177], v[46:49]
	v_mfma_f32_16x16x32_bf16 v[42:45], v[138:141], v[170:173], v[42:45]
	v_mfma_f32_16x16x32_bf16 v[42:45], v[142:145], v[174:177], v[42:45]
	v_mfma_f32_16x16x32_bf16 v[30:33], v[130:133], v[196:199], v[30:33]
	v_mfma_f32_16x16x32_bf16 v[30:33], v[134:137], v[200:203], v[30:33]
	v_mfma_f32_16x16x32_bf16 v[26:29], v[138:141], v[196:199], v[26:29]
	v_mfma_f32_16x16x32_bf16 v[26:29], v[142:145], v[200:203], v[26:29]
	v_mfma_f32_16x16x32_bf16 v[14:17], v[130:133], v[214:217], v[14:17]
	v_mfma_f32_16x16x32_bf16 v[14:17], v[134:137], v[218:221], v[14:17]
	v_mfma_f32_16x16x32_bf16 v[10:13], v[138:141], v[214:217], v[10:13]
	v_mfma_f32_16x16x32_bf16 v[10:13], v[142:145], v[218:221], v[10:13]
	v_mfma_f32_16x16x32_bf16 v[54:57], v[146:149], v[162:165], v[54:57]
	v_mfma_f32_16x16x32_bf16 v[54:57], v[150:153], v[166:169], v[54:57]
	v_mfma_f32_16x16x32_bf16 v[50:53], v[154:157], v[162:165], v[50:53]
	v_mfma_f32_16x16x32_bf16 v[50:53], v[158:161], v[166:169], v[50:53]
	v_mfma_f32_16x16x32_bf16 v[38:41], v[146:149], v[170:173], v[38:41]
	v_mfma_f32_16x16x32_bf16 v[38:41], v[150:153], v[174:177], v[38:41]
	v_mfma_f32_16x16x32_bf16 v[34:37], v[154:157], v[170:173], v[34:37]
	v_mfma_f32_16x16x32_bf16 v[34:37], v[158:161], v[174:177], v[34:37]
	v_mfma_f32_16x16x32_bf16 v[22:25], v[146:149], v[196:199], v[22:25]
	v_mfma_f32_16x16x32_bf16 v[22:25], v[150:153], v[200:203], v[22:25]
	v_mfma_f32_16x16x32_bf16 v[18:21], v[154:157], v[196:199], v[18:21]
	v_mfma_f32_16x16x32_bf16 v[18:21], v[158:161], v[200:203], v[18:21]
	v_mfma_f32_16x16x32_bf16 v[6:9], v[146:149], v[214:217], v[6:9]
	v_mfma_f32_16x16x32_bf16 v[6:9], v[150:153], v[218:221], v[6:9]
	v_mfma_f32_16x16x32_bf16 v[2:5], v[154:157], v[214:217], v[2:5]
	v_mfma_f32_16x16x32_bf16 v[2:5], v[158:161], v[218:221], v[2:5]
	s_barrier
	s_add_i32 s72, s72, 2
	s_add_u32 s36, s36, 0x8000
	s_addc_u32 s37, s37, 0
	s_add_u32 s70, s70, 0x8000
	s_addc_u32 s71, s71, 0
	s_cmp_gt_u32 s72, 61
	s_cbranch_scc0 .LBB0_1088
	s_and_b64 vcc, exec, s[20:21]
	s_cbranch_vccz .LBB0_1091
	s_barrier

.LBB0_1215:
	ds_read_b128 v[160:163], v154
	ds_read_b128 v[164:167], v154 offset:1024
	ds_read_b128 v[168:171], v154 offset:2048
	ds_read_b128 v[172:175], v154 offset:3072
	ds_read_b128 v[176:179], v155
	ds_read_b128 v[180:183], v155 offset:1024
	ds_read_b128 v[184:187], v155 offset:2048
	ds_read_b128 v[188:191], v155 offset:3072
	s_add_u32 s30, s28, 0xfff04000
	s_addc_u32 s31, s29, -1
	s_cmp_eq_u32 s61, 60
	s_cselect_b32 s36, s56, s30
	s_cselect_b32 s37, s21, s31
	s_cselect_b32 s34, s57, s59
	s_cselect_b32 s35, s19, s60
	s_add_u32 s30, s36, 0x4000
	s_addc_u32 s31, s37, 0
	s_add_i32 m0, s39, 0xc000
	ds_read_b128 v[192:195], v156
	ds_read_b128 v[196:199], v156 offset:1024
	ds_read_b128 v[200:203], v156 offset:2048
	ds_read_b128 v[204:207], v156 offset:3072
	ds_read_b128 v[208:211], v156 offset:4096
	ds_read_b128 v[212:215], v156 offset:5120
	ds_read_b128 v[216:219], v156 offset:6144
	ds_read_b128 v[220:223], v156 offset:7168
	global_load_lds_dwordx4 v140, s[28:29]
	s_add_i32 m0, s39, 0xe000
	s_nop 0
	global_load_lds_dwordx4 v142, s[28:29]
	s_waitcnt vmcnt(8) lgkmcnt(0)
	s_barrier
	v_mfma_f32_16x16x32_bf16 v[126:129], v[160:163], v[192:195], v[126:129]
	v_mfma_f32_16x16x32_bf16 v[126:129], v[164:167], v[196:199], v[126:129]
	v_mfma_f32_16x16x32_bf16 v[122:125], v[168:171], v[192:195], v[122:125]
	v_mfma_f32_16x16x32_bf16 v[122:125], v[172:175], v[196:199], v[122:125]
	v_mfma_f32_16x16x32_bf16 v[110:113], v[160:163], v[200:203], v[110:113]
	v_mfma_f32_16x16x32_bf16 v[110:113], v[164:167], v[204:207], v[110:113]
	v_mfma_f32_16x16x32_bf16 v[106:109], v[168:171], v[200:203], v[106:109]
	v_mfma_f32_16x16x32_bf16 v[106:109], v[172:175], v[204:207], v[106:109]
	v_mfma_f32_16x16x32_bf16 v[94:97], v[160:163], v[208:211], v[94:97]
	v_mfma_f32_16x16x32_bf16 v[94:97], v[164:167], v[212:215], v[94:97]
	v_mfma_f32_16x16x32_bf16 v[90:93], v[168:171], v[208:211], v[90:93]
	v_mfma_f32_16x16x32_bf16 v[90:93], v[172:175], v[212:215], v[90:93]
	v_mfma_f32_16x16x32_bf16 v[78:81], v[160:163], v[216:219], v[78:81]
	v_mfma_f32_16x16x32_bf16 v[78:81], v[164:167], v[220:223], v[78:81]
	v_mfma_f32_16x16x32_bf16 v[74:77], v[168:171], v[216:219], v[74:77]
	v_mfma_f32_16x16x32_bf16 v[74:77], v[172:175], v[220:223], v[74:77]
	v_mfma_f32_16x16x32_bf16 v[118:121], v[176:179], v[192:195], v[118:121]
	v_mfma_f32_16x16x32_bf16 v[118:121], v[180:183], v[196:199], v[118:121]
	v_mfma_f32_16x16x32_bf16 v[114:117], v[184:187], v[192:195], v[114:117]
	v_mfma_f32_16x16x32_bf16 v[114:117], v[188:191], v[196:199], v[114:117]
	v_mfma_f32_16x16x32_bf16 v[102:105], v[176:179], v[200:203], v[102:105]
	v_mfma_f32_16x16x32_bf16 v[102:105], v[180:183], v[204:207], v[102:105]
	v_mfma_f32_16x16x32_bf16 v[98:101], v[184:187], v[200:203], v[98:101]
	v_mfma_f32_16x16x32_bf16 v[98:101], v[188:191], v[204:207], v[98:101]
	v_mfma_f32_16x16x32_bf16 v[86:89], v[176:179], v[208:211], v[86:89]
	v_mfma_f32_16x16x32_bf16 v[86:89], v[180:183], v[212:215], v[86:89]
	v_mfma_f32_16x16x32_bf16 v[82:85], v[184:187], v[208:211], v[82:85]
	v_mfma_f32_16x16x32_bf16 v[82:85], v[188:191], v[212:215], v[82:85]
	v_mfma_f32_16x16x32_bf16 v[70:73], v[176:179], v[216:219], v[70:73]
	v_mfma_f32_16x16x32_bf16 v[70:73], v[180:183], v[220:223], v[70:73]
	v_mfma_f32_16x16x32_bf16 v[66:69], v[184:187], v[216:219], v[66:69]
	v_mfma_f32_16x16x32_bf16 v[66:69], v[188:191], v[220:223], v[66:69]
	s_barrier
	s_add_i32 s62, s47, s38
	s_mov_b32 m0, s62
	ds_read_b128 v[192:195], v156 offset:16384
	ds_read_b128 v[196:199], v156 offset:17408
	ds_read_b128 v[200:203], v156 offset:18432
	ds_read_b128 v[204:207], v156 offset:19456
	ds_read_b128 v[208:211], v156 offset:20480
	ds_read_b128 v[212:215], v156 offset:21504
	ds_read_b128 v[216:219], v156 offset:22528
	ds_read_b128 v[220:223], v156 offset:23552
	global_load_lds_dwordx4 v134, s[34:35]
	s_add_i32 m0, s62, 0x2000
	s_add_u32 s62, s34, 0x100000
	s_addc_u32 s63, s35, 0
	s_add_i32 s64, s54, s38
	global_load_lds_dwordx4 v130, s[34:35]
	s_mov_b32 m0, s64
	s_nop 0
	global_load_lds_dwordx4 v134, s[62:63]
	s_add_i32 m0, s64, 0x2000
	s_nop 0
	global_load_lds_dwordx4 v130, s[62:63]
	s_mov_b32 m0, s39
	s_nop 0
	global_load_lds_dwordx4 v136, s[36:37]
	s_mov_b32 m0, s40
	s_nop 0
	global_load_lds_dwordx4 v132, s[36:37]
	s_waitcnt vmcnt(8) lgkmcnt(0)
	s_barrier
	v_mfma_f32_16x16x32_bf16 v[62:65], v[160:163], v[192:195], v[62:65]
	v_mfma_f32_16x16x32_bf16 v[62:65], v[164:167], v[196:199], v[62:65]
	v_mfma_f32_16x16x32_bf16 v[58:61], v[168:171], v[192:195], v[58:61]
	v_mfma_f32_16x16x32_bf16 v[58:61], v[172:175], v[196:199], v[58:61]
	v_mfma_f32_16x16x32_bf16 v[46:49], v[160:163], v[200:203], v[46:49]
	v_mfma_f32_16x16x32_bf16 v[46:49], v[164:167], v[204:207], v[46:49]
	v_mfma_f32_16x16x32_bf16 v[42:45], v[168:171], v[200:203], v[42:45]
	v_mfma_f32_16x16x32_bf16 v[42:45], v[172:175], v[204:207], v[42:45]
	v_mfma_f32_16x16x32_bf16 v[30:33], v[160:163], v[208:211], v[30:33]
	v_mfma_f32_16x16x32_bf16 v[30:33], v[164:167], v[212:215], v[30:33]
	v_mfma_f32_16x16x32_bf16 v[26:29], v[168:171], v[208:211], v[26:29]
	v_mfma_f32_16x16x32_bf16 v[26:29], v[172:175], v[212:215], v[26:29]
	v_mfma_f32_16x16x32_bf16 v[14:17], v[160:163], v[216:219], v[14:17]
	v_mfma_f32_16x16x32_bf16 v[14:17], v[164:167], v[220:223], v[14:17]
	v_mfma_f32_16x16x32_bf16 v[10:13], v[168:171], v[216:219], v[10:13]
	v_mfma_f32_16x16x32_bf16 v[10:13], v[172:175], v[220:223], v[10:13]
	v_mfma_f32_16x16x32_bf16 v[54:57], v[176:179], v[192:195], v[54:57]
	v_mfma_f32_16x16x32_bf16 v[54:57], v[180:183], v[196:199], v[54:57]
	v_mfma_f32_16x16x32_bf16 v[50:53], v[184:187], v[192:195], v[50:53]
	v_mfma_f32_16x16x32_bf16 v[50:53], v[188:191], v[196:199], v[50:53]
	v_mfma_f32_16x16x32_bf16 v[38:41], v[176:179], v[200:203], v[38:41]
	v_mfma_f32_16x16x32_bf16 v[38:41], v[180:183], v[204:207], v[38:41]
	v_mfma_f32_16x16x32_bf16 v[34:37], v[184:187], v[200:203], v[34:37]
	v_mfma_f32_16x16x32_bf16 v[34:37], v[188:191], v[204:207], v[34:37]
	v_mfma_f32_16x16x32_bf16 v[22:25], v[176:179], v[208:211], v[22:25]
	v_mfma_f32_16x16x32_bf16 v[22:25], v[180:183], v[212:215], v[22:25]
	v_mfma_f32_16x16x32_bf16 v[18:21], v[184:187], v[208:211], v[18:21]
	v_mfma_f32_16x16x32_bf16 v[18:21], v[188:191], v[212:215], v[18:21]
	v_mfma_f32_16x16x32_bf16 v[6:9], v[176:179], v[216:219], v[6:9]
	v_mfma_f32_16x16x32_bf16 v[6:9], v[180:183], v[220:223], v[6:9]
	v_mfma_f32_16x16x32_bf16 v[2:5], v[184:187], v[216:219], v[2:5]
	v_mfma_f32_16x16x32_bf16 v[2:5], v[188:191], v[220:223], v[2:5]
	s_barrier
	s_add_i32 s62, 0, 0x18000
	v_add_u32_e32 v138, s62, v153
	s_add_i32 s63, 0, 0x1c000
	ds_read_b128 v[160:163], v138
	ds_read_b128 v[164:167], v138 offset:1024
	ds_read_b128 v[168:171], v138 offset:2048
	ds_read_b128 v[172:175], v138 offset:3072
	v_add_u32_e32 v138, s63, v153
	ds_read_b128 v[176:179], v138
	ds_read_b128 v[180:183], v138 offset:1024
	ds_read_b128 v[184:187], v138 offset:2048
	ds_read_b128 v[188:191], v138 offset:3072
	s_add_u32 s36, s36, 0x100000
	s_addc_u32 s37, s37, 0
	s_mov_b32 m0, s41
	ds_read_b128 v[192:195], v156 offset:32768
	ds_read_b128 v[196:199], v156 offset:33792
	ds_read_b128 v[200:203], v156 offset:34816
	ds_read_b128 v[204:207], v156 offset:35840
	ds_read_b128 v[208:211], v156 offset:36864
	ds_read_b128 v[212:215], v156 offset:37888
	ds_read_b128 v[216:219], v156 offset:38912
	ds_read_b128 v[220:223], v156 offset:39936
	global_load_lds_dwordx4 v136, s[36:37]
	s_mov_b32 m0, s42
	s_nop 0
	global_load_lds_dwordx4 v132, s[36:37]
	s_waitcnt vmcnt(8) lgkmcnt(0)
	s_barrier
	v_mfma_f32_16x16x32_bf16 v[126:129], v[160:163], v[192:195], v[126:129]
	v_mfma_f32_16x16x32_bf16 v[126:129], v[164:167], v[196:199], v[126:129]
	v_mfma_f32_16x16x32_bf16 v[122:125], v[168:171], v[192:195], v[122:125]
	v_mfma_f32_16x16x32_bf16 v[122:125], v[172:175], v[196:199], v[122:125]
	v_mfma_f32_16x16x32_bf16 v[110:113], v[160:163], v[200:203], v[110:113]
	v_mfma_f32_16x16x32_bf16 v[110:113], v[164:167], v[204:207], v[110:113]
	v_mfma_f32_16x16x32_bf16 v[106:109], v[168:171], v[200:203], v[106:109]
	v_mfma_f32_16x16x32_bf16 v[106:109], v[172:175], v[204:207], v[106:109]
	v_mfma_f32_16x16x32_bf16 v[94:97], v[160:163], v[208:211], v[94:97]
	v_mfma_f32_16x16x32_bf16 v[94:97], v[164:167], v[212:215], v[94:97]
	v_mfma_f32_16x16x32_bf16 v[90:93], v[168:171], v[208:211], v[90:93]
	v_mfma_f32_16x16x32_bf16 v[90:93], v[172:175], v[212:215], v[90:93]
	v_mfma_f32_16x16x32_bf16 v[78:81], v[160:163], v[216:219], v[78:81]
	v_mfma_f32_16x16x32_bf16 v[78:81], v[164:167], v[220:223], v[78:81]
	v_mfma_f32_16x16x32_bf16 v[74:77], v[168:171], v[216:219], v[74:77]
	v_mfma_f32_16x16x32_bf16 v[74:77], v[172:175], v[220:223], v[74:77]
	v_mfma_f32_16x16x32_bf16 v[118:121], v[176:179], v[192:195], v[118:121]
	v_mfma_f32_16x16x32_bf16 v[118:121], v[180:183], v[196:199], v[118:121]
	v_mfma_f32_16x16x32_bf16 v[114:117], v[184:187], v[192:195], v[114:117]
	v_mfma_f32_16x16x32_bf16 v[114:117], v[188:191], v[196:199], v[114:117]
	v_mfma_f32_16x16x32_bf16 v[102:105], v[176:179], v[200:203], v[102:105]
	v_mfma_f32_16x16x32_bf16 v[102:105], v[180:183], v[204:207], v[102:105]
	v_mfma_f32_16x16x32_bf16 v[98:101], v[184:187], v[200:203], v[98:101]
	v_mfma_f32_16x16x32_bf16 v[98:101], v[188:191], v[204:207], v[98:101]
	v_mfma_f32_16x16x32_bf16 v[86:89], v[176:179], v[208:211], v[86:89]
	v_mfma_f32_16x16x32_bf16 v[86:89], v[180:183], v[212:215], v[86:89]
	v_mfma_f32_16x16x32_bf16 v[82:85], v[184:187], v[208:211], v[82:85]
	v_mfma_f32_16x16x32_bf16 v[82:85], v[188:191], v[212:215], v[82:85]
	v_mfma_f32_16x16x32_bf16 v[70:73], v[176:179], v[216:219], v[70:73]
	v_mfma_f32_16x16x32_bf16 v[70:73], v[180:183], v[220:223], v[70:73]
	v_mfma_f32_16x16x32_bf16 v[66:69], v[184:187], v[216:219], v[66:69]
	v_mfma_f32_16x16x32_bf16 v[66:69], v[188:191], v[220:223], v[66:69]
	s_barrier
	s_add_u32 s36, s34, 0x4000
	s_addc_u32 s37, s35, 0
	s_add_i32 s62, s62, s38
	s_mov_b32 m0, s62
	ds_read_b128 v[192:195], v156 offset:49152
	ds_read_b128 v[196:199], v156 offset:50176
	ds_read_b128 v[200:203], v156 offset:51200
	ds_read_b128 v[204:207], v156 offset:52224
	ds_read_b128 v[208:211], v156 offset:53248
	ds_read_b128 v[212:215], v156 offset:54272
	ds_read_b128 v[216:219], v156 offset:55296
	ds_read_b128 v[220:223], v156 offset:56320
	global_load_lds_dwordx4 v134, s[36:37]
	s_add_i32 m0, s62, 0x2000
	s_add_u32 s34, s34, 0x104000
	s_addc_u32 s35, s35, 0
	global_load_lds_dwordx4 v130, s[36:37]
	s_add_i32 s36, s63, s38
	s_mov_b32 m0, s36
	s_nop 0
	global_load_lds_dwordx4 v134, s[34:35]
	s_add_i32 m0, s36, 0x2000
	s_nop 0
	global_load_lds_dwordx4 v130, s[34:35]
	s_mov_b32 m0, s45
	s_nop 0
	global_load_lds_dwordx4 v136, s[30:31]
	s_mov_b32 m0, s46
	s_nop 0
	global_load_lds_dwordx4 v132, s[30:31]
	s_waitcnt vmcnt(8) lgkmcnt(0)
	s_barrier
	v_mfma_f32_16x16x32_bf16 v[62:65], v[160:163], v[192:195], v[62:65]
	v_mfma_f32_16x16x32_bf16 v[62:65], v[164:167], v[196:199], v[62:65]
	v_mfma_f32_16x16x32_bf16 v[58:61], v[168:171], v[192:195], v[58:61]
	v_mfma_f32_16x16x32_bf16 v[58:61], v[172:175], v[196:199], v[58:61]
	v_mfma_f32_16x16x32_bf16 v[46:49], v[160:163], v[200:203], v[46:49]
	v_mfma_f32_16x16x32_bf16 v[46:49], v[164:167], v[204:207], v[46:49]
	v_mfma_f32_16x16x32_bf16 v[42:45], v[168:171], v[200:203], v[42:45]
	v_mfma_f32_16x16x32_bf16 v[42:45], v[172:175], v[204:207], v[42:45]
	v_mfma_f32_16x16x32_bf16 v[30:33], v[160:163], v[208:211], v[30:33]
	v_mfma_f32_16x16x32_bf16 v[30:33], v[164:167], v[212:215], v[30:33]
	v_mfma_f32_16x16x32_bf16 v[26:29], v[168:171], v[208:211], v[26:29]
	v_mfma_f32_16x16x32_bf16 v[26:29], v[172:175], v[212:215], v[26:29]
	v_mfma_f32_16x16x32_bf16 v[14:17], v[160:163], v[216:219], v[14:17]
	v_mfma_f32_16x16x32_bf16 v[14:17], v[164:167], v[220:223], v[14:17]
	v_mfma_f32_16x16x32_bf16 v[10:13], v[168:171], v[216:219], v[10:13]
	v_mfma_f32_16x16x32_bf16 v[10:13], v[172:175], v[220:223], v[10:13]
	v_mfma_f32_16x16x32_bf16 v[54:57], v[176:179], v[192:195], v[54:57]
	v_mfma_f32_16x16x32_bf16 v[54:57], v[180:183], v[196:199], v[54:57]
	v_mfma_f32_16x16x32_bf16 v[50:53], v[184:187], v[192:195], v[50:53]
	v_mfma_f32_16x16x32_bf16 v[50:53], v[188:191], v[196:199], v[50:53]
	v_mfma_f32_16x16x32_bf16 v[38:41], v[176:179], v[200:203], v[38:41]
	v_mfma_f32_16x16x32_bf16 v[38:41], v[180:183], v[204:207], v[38:41]
	v_mfma_f32_16x16x32_bf16 v[34:37], v[184:187], v[200:203], v[34:37]
	v_mfma_f32_16x16x32_bf16 v[34:37], v[188:191], v[204:207], v[34:37]
	v_mfma_f32_16x16x32_bf16 v[22:25], v[176:179], v[208:211], v[22:25]
	v_mfma_f32_16x16x32_bf16 v[22:25], v[180:183], v[212:215], v[22:25]
	v_mfma_f32_16x16x32_bf16 v[18:21], v[184:187], v[208:211], v[18:21]
	v_mfma_f32_16x16x32_bf16 v[18:21], v[188:191], v[212:215], v[18:21]
	v_mfma_f32_16x16x32_bf16 v[6:9], v[176:179], v[216:219], v[6:9]
	v_mfma_f32_16x16x32_bf16 v[6:9], v[180:183], v[220:223], v[6:9]
	v_mfma_f32_16x16x32_bf16 v[2:5], v[184:187], v[216:219], v[2:5]
	v_mfma_f32_16x16x32_bf16 v[2:5], v[188:191], v[220:223], v[2:5]
	s_barrier
	s_add_i32 s61, s61, 2
	s_add_u32 s28, s28, 0x8000
	s_addc_u32 s29, s29, 0
	s_add_u32 s59, s59, 0x8000
	s_addc_u32 s60, s60, 0
	s_cmp_gt_u32 s61, 61
	s_cbranch_scc0 .LBB0_1215
	s_and_b64 vcc, exec, s[16:17]
	s_cbranch_vccz .LBB0_1218
	s_barrier

.LBB0_1292:
	ds_read_b128 v[130:133], v206
	ds_read_b128 v[134:137], v206 offset:1024
	ds_read_b128 v[138:141], v206 offset:2048
	ds_read_b128 v[142:145], v206 offset:3072
	ds_read_b128 v[146:149], v207
	ds_read_b128 v[150:153], v207 offset:1024
	ds_read_b128 v[176:179], v207 offset:2048
	ds_read_b128 v[180:183], v207 offset:3072
	s_add_u32 s42, s40, 0xffc04000
	s_addc_u32 s43, s41, -1
	s_cmpk_eq_i32 s66, 0xfc
	s_cselect_b32 s46, s29, s42
	s_cselect_b32 s47, s14, s43
	s_cselect_b32 s44, s37, s39
	s_cselect_b32 s45, s27, s65
	s_add_u32 s42, s46, 0x4000
	s_addc_u32 s43, s47, 0
	s_add_i32 m0, s53, 0xc000
	ds_read_b128 v[184:187], v208
	ds_read_b128 v[188:191], v208 offset:1024
	ds_read_b128 v[192:195], v208 offset:2048
	ds_read_b128 v[196:199], v208 offset:3072
	ds_read_b128 v[210:213], v208 offset:4096
	ds_read_b128 v[214:217], v208 offset:5120
	ds_read_b128 v[218:221], v208 offset:6144
	ds_read_b128 v[222:225], v208 offset:7168
	global_load_lds_dwordx4 v166, s[40:41]
	s_add_i32 m0, s53, 0xe000
	s_nop 0
	global_load_lds_dwordx4 v168, s[40:41]
	s_waitcnt vmcnt(8) lgkmcnt(0)
	s_barrier
	v_mfma_f32_16x16x32_bf16 v[126:129], v[130:133], v[184:187], v[126:129]
	v_mfma_f32_16x16x32_bf16 v[126:129], v[134:137], v[188:191], v[126:129]
	v_mfma_f32_16x16x32_bf16 v[122:125], v[138:141], v[184:187], v[122:125]
	v_mfma_f32_16x16x32_bf16 v[122:125], v[142:145], v[188:191], v[122:125]
	v_mfma_f32_16x16x32_bf16 v[110:113], v[130:133], v[192:195], v[110:113]
	v_mfma_f32_16x16x32_bf16 v[110:113], v[134:137], v[196:199], v[110:113]
	v_mfma_f32_16x16x32_bf16 v[106:109], v[138:141], v[192:195], v[106:109]
	v_mfma_f32_16x16x32_bf16 v[106:109], v[142:145], v[196:199], v[106:109]
	v_mfma_f32_16x16x32_bf16 v[94:97], v[130:133], v[210:213], v[94:97]
	v_mfma_f32_16x16x32_bf16 v[94:97], v[134:137], v[214:217], v[94:97]
	v_mfma_f32_16x16x32_bf16 v[90:93], v[138:141], v[210:213], v[90:93]
	v_mfma_f32_16x16x32_bf16 v[90:93], v[142:145], v[214:217], v[90:93]
	v_mfma_f32_16x16x32_bf16 v[78:81], v[130:133], v[218:221], v[78:81]
	v_mfma_f32_16x16x32_bf16 v[78:81], v[134:137], v[222:225], v[78:81]
	v_mfma_f32_16x16x32_bf16 v[74:77], v[138:141], v[218:221], v[74:77]
	v_mfma_f32_16x16x32_bf16 v[74:77], v[142:145], v[222:225], v[74:77]
	v_mfma_f32_16x16x32_bf16 v[118:121], v[146:149], v[184:187], v[118:121]
	v_mfma_f32_16x16x32_bf16 v[118:121], v[150:153], v[188:191], v[118:121]
	v_mfma_f32_16x16x32_bf16 v[114:117], v[176:179], v[184:187], v[114:117]
	v_mfma_f32_16x16x32_bf16 v[114:117], v[180:183], v[188:191], v[114:117]
	v_mfma_f32_16x16x32_bf16 v[102:105], v[146:149], v[192:195], v[102:105]
	v_mfma_f32_16x16x32_bf16 v[102:105], v[150:153], v[196:199], v[102:105]
	v_mfma_f32_16x16x32_bf16 v[98:101], v[176:179], v[192:195], v[98:101]
	v_mfma_f32_16x16x32_bf16 v[98:101], v[180:183], v[196:199], v[98:101]
	v_mfma_f32_16x16x32_bf16 v[86:89], v[146:149], v[210:213], v[86:89]
	v_mfma_f32_16x16x32_bf16 v[86:89], v[150:153], v[214:217], v[86:89]
	v_mfma_f32_16x16x32_bf16 v[82:85], v[176:179], v[210:213], v[82:85]
	v_mfma_f32_16x16x32_bf16 v[82:85], v[180:183], v[214:217], v[82:85]
	v_mfma_f32_16x16x32_bf16 v[70:73], v[146:149], v[218:221], v[70:73]
	v_mfma_f32_16x16x32_bf16 v[70:73], v[150:153], v[222:225], v[70:73]
	v_mfma_f32_16x16x32_bf16 v[66:69], v[176:179], v[218:221], v[66:69]
	v_mfma_f32_16x16x32_bf16 v[66:69], v[180:183], v[222:225], v[66:69]
	s_barrier
	s_add_i32 s67, s62, s52
	s_mov_b32 m0, s67
	ds_read_b128 v[184:187], v208 offset:16384
	ds_read_b128 v[188:191], v208 offset:17408
	ds_read_b128 v[192:195], v208 offset:18432
	ds_read_b128 v[196:199], v208 offset:19456
	ds_read_b128 v[210:213], v208 offset:20480
	ds_read_b128 v[214:217], v208 offset:21504
	ds_read_b128 v[218:221], v208 offset:22528
	ds_read_b128 v[222:225], v208 offset:23552
	global_load_lds_dwordx4 v156, s[44:45]
	s_add_i32 m0, s67, 0x2000
	s_add_u32 s68, s44, 0x400000
	s_addc_u32 s69, s45, 0
	s_add_i32 s67, s63, s52
	global_load_lds_dwordx4 v160, s[44:45]
	s_mov_b32 m0, s67
	s_nop 0
	global_load_lds_dwordx4 v156, s[68:69]
	s_add_i32 m0, s67, 0x2000
	s_nop 0
	global_load_lds_dwordx4 v160, s[68:69]
	s_mov_b32 m0, s53
	s_nop 0
	global_load_lds_dwordx4 v154, s[46:47]
	s_mov_b32 m0, s54
	s_nop 0
	global_load_lds_dwordx4 v158, s[46:47]
	s_waitcnt vmcnt(8) lgkmcnt(0)
	s_barrier
	v_mfma_f32_16x16x32_bf16 v[62:65], v[130:133], v[184:187], v[62:65]
	v_mfma_f32_16x16x32_bf16 v[62:65], v[134:137], v[188:191], v[62:65]
	v_mfma_f32_16x16x32_bf16 v[58:61], v[138:141], v[184:187], v[58:61]
	v_mfma_f32_16x16x32_bf16 v[58:61], v[142:145], v[188:191], v[58:61]
	v_mfma_f32_16x16x32_bf16 v[46:49], v[130:133], v[192:195], v[46:49]
	v_mfma_f32_16x16x32_bf16 v[46:49], v[134:137], v[196:199], v[46:49]
	v_mfma_f32_16x16x32_bf16 v[42:45], v[138:141], v[192:195], v[42:45]
	v_mfma_f32_16x16x32_bf16 v[42:45], v[142:145], v[196:199], v[42:45]
	v_mfma_f32_16x16x32_bf16 v[30:33], v[130:133], v[210:213], v[30:33]
	v_mfma_f32_16x16x32_bf16 v[30:33], v[134:137], v[214:217], v[30:33]
	v_mfma_f32_16x16x32_bf16 v[26:29], v[138:141], v[210:213], v[26:29]
	v_mfma_f32_16x16x32_bf16 v[26:29], v[142:145], v[214:217], v[26:29]
	v_mfma_f32_16x16x32_bf16 v[14:17], v[130:133], v[218:221], v[14:17]
	v_mfma_f32_16x16x32_bf16 v[14:17], v[134:137], v[222:225], v[14:17]
	v_mfma_f32_16x16x32_bf16 v[10:13], v[138:141], v[218:221], v[10:13]
	v_mfma_f32_16x16x32_bf16 v[10:13], v[142:145], v[222:225], v[10:13]
	v_mfma_f32_16x16x32_bf16 v[54:57], v[146:149], v[184:187], v[54:57]
	v_mfma_f32_16x16x32_bf16 v[54:57], v[150:153], v[188:191], v[54:57]
	v_mfma_f32_16x16x32_bf16 v[50:53], v[176:179], v[184:187], v[50:53]
	v_mfma_f32_16x16x32_bf16 v[50:53], v[180:183], v[188:191], v[50:53]
	v_mfma_f32_16x16x32_bf16 v[38:41], v[146:149], v[192:195], v[38:41]
	v_mfma_f32_16x16x32_bf16 v[38:41], v[150:153], v[196:199], v[38:41]
	v_mfma_f32_16x16x32_bf16 v[34:37], v[176:179], v[192:195], v[34:37]
	v_mfma_f32_16x16x32_bf16 v[34:37], v[180:183], v[196:199], v[34:37]
	v_mfma_f32_16x16x32_bf16 v[22:25], v[146:149], v[210:213], v[22:25]
	v_mfma_f32_16x16x32_bf16 v[22:25], v[150:153], v[214:217], v[22:25]
	v_mfma_f32_16x16x32_bf16 v[18:21], v[176:179], v[210:213], v[18:21]
	v_mfma_f32_16x16x32_bf16 v[18:21], v[180:183], v[214:217], v[18:21]
	v_mfma_f32_16x16x32_bf16 v[6:9], v[146:149], v[218:221], v[6:9]
	v_mfma_f32_16x16x32_bf16 v[6:9], v[150:153], v[222:225], v[6:9]
	v_mfma_f32_16x16x32_bf16 v[2:5], v[176:179], v[218:221], v[2:5]
	v_mfma_f32_16x16x32_bf16 v[2:5], v[180:183], v[222:225], v[2:5]
	s_barrier
	s_add_i32 s67, 0, 0x18000
	s_add_i32 s68, 0, 0x1c000
	v_add_u32_e32 v142, s67, v203
	v_add_u32_e32 v162, s68, v203
	ds_read_b128 v[130:133], v142
	ds_read_b128 v[134:137], v142 offset:1024
	ds_read_b128 v[138:141], v142 offset:2048
	ds_read_b128 v[142:145], v142 offset:3072
	ds_read_b128 v[146:149], v162
	ds_read_b128 v[150:153], v162 offset:1024
	ds_read_b128 v[176:179], v162 offset:2048
	ds_read_b128 v[180:183], v162 offset:3072
	s_add_u32 s46, s46, 0x400000
	s_addc_u32 s47, s47, 0
	s_mov_b32 m0, s55
	ds_read_b128 v[184:187], v208 offset:32768
	ds_read_b128 v[188:191], v208 offset:33792
	ds_read_b128 v[192:195], v208 offset:34816
	ds_read_b128 v[196:199], v208 offset:35840
	ds_read_b128 v[210:213], v208 offset:36864
	ds_read_b128 v[214:217], v208 offset:37888
	ds_read_b128 v[218:221], v208 offset:38912
	ds_read_b128 v[222:225], v208 offset:39936
	global_load_lds_dwordx4 v154, s[46:47]
	s_mov_b32 m0, s56
	s_nop 0
	global_load_lds_dwordx4 v158, s[46:47]
	s_waitcnt vmcnt(8) lgkmcnt(0)
	s_barrier
	v_mfma_f32_16x16x32_bf16 v[126:129], v[130:133], v[184:187], v[126:129]
	v_mfma_f32_16x16x32_bf16 v[126:129], v[134:137], v[188:191], v[126:129]
	v_mfma_f32_16x16x32_bf16 v[122:125], v[138:141], v[184:187], v[122:125]
	v_mfma_f32_16x16x32_bf16 v[122:125], v[142:145], v[188:191], v[122:125]
	v_mfma_f32_16x16x32_bf16 v[110:113], v[130:133], v[192:195], v[110:113]
	v_mfma_f32_16x16x32_bf16 v[110:113], v[134:137], v[196:199], v[110:113]
	v_mfma_f32_16x16x32_bf16 v[106:109], v[138:141], v[192:195], v[106:109]
	v_mfma_f32_16x16x32_bf16 v[106:109], v[142:145], v[196:199], v[106:109]
	v_mfma_f32_16x16x32_bf16 v[94:97], v[130:133], v[210:213], v[94:97]
	v_mfma_f32_16x16x32_bf16 v[94:97], v[134:137], v[214:217], v[94:97]
	v_mfma_f32_16x16x32_bf16 v[90:93], v[138:141], v[210:213], v[90:93]
	v_mfma_f32_16x16x32_bf16 v[90:93], v[142:145], v[214:217], v[90:93]
	v_mfma_f32_16x16x32_bf16 v[78:81], v[130:133], v[218:221], v[78:81]
	v_mfma_f32_16x16x32_bf16 v[78:81], v[134:137], v[222:225], v[78:81]
	v_mfma_f32_16x16x32_bf16 v[74:77], v[138:141], v[218:221], v[74:77]
	v_mfma_f32_16x16x32_bf16 v[74:77], v[142:145], v[222:225], v[74:77]
	v_mfma_f32_16x16x32_bf16 v[118:121], v[146:149], v[184:187], v[118:121]
	v_mfma_f32_16x16x32_bf16 v[118:121], v[150:153], v[188:191], v[118:121]
	v_mfma_f32_16x16x32_bf16 v[114:117], v[176:179], v[184:187], v[114:117]
	v_mfma_f32_16x16x32_bf16 v[114:117], v[180:183], v[188:191], v[114:117]
	v_mfma_f32_16x16x32_bf16 v[102:105], v[146:149], v[192:195], v[102:105]
	v_mfma_f32_16x16x32_bf16 v[102:105], v[150:153], v[196:199], v[102:105]
	v_mfma_f32_16x16x32_bf16 v[98:101], v[176:179], v[192:195], v[98:101]
	v_mfma_f32_16x16x32_bf16 v[98:101], v[180:183], v[196:199], v[98:101]
	v_mfma_f32_16x16x32_bf16 v[86:89], v[146:149], v[210:213], v[86:89]
	v_mfma_f32_16x16x32_bf16 v[86:89], v[150:153], v[214:217], v[86:89]
	v_mfma_f32_16x16x32_bf16 v[82:85], v[176:179], v[210:213], v[82:85]
	v_mfma_f32_16x16x32_bf16 v[82:85], v[180:183], v[214:217], v[82:85]
	v_mfma_f32_16x16x32_bf16 v[70:73], v[146:149], v[218:221], v[70:73]
	v_mfma_f32_16x16x32_bf16 v[70:73], v[150:153], v[222:225], v[70:73]
	v_mfma_f32_16x16x32_bf16 v[66:69], v[176:179], v[218:221], v[66:69]
	v_mfma_f32_16x16x32_bf16 v[66:69], v[180:183], v[222:225], v[66:69]
	s_barrier
	s_add_u32 s46, s44, 0x4000
	s_addc_u32 s47, s45, 0
	s_add_i32 s67, s67, s52
	s_mov_b32 m0, s67
	ds_read_b128 v[184:187], v208 offset:49152
	ds_read_b128 v[188:191], v208 offset:50176
	ds_read_b128 v[192:195], v208 offset:51200
	ds_read_b128 v[196:199], v208 offset:52224
	ds_read_b128 v[210:213], v208 offset:53248
	ds_read_b128 v[214:217], v208 offset:54272
	ds_read_b128 v[218:221], v208 offset:55296
	ds_read_b128 v[222:225], v208 offset:56320
	global_load_lds_dwordx4 v156, s[46:47]
	s_add_i32 m0, s67, 0x2000
	s_add_u32 s44, s44, 0x404000
	s_addc_u32 s45, s45, 0
	global_load_lds_dwordx4 v160, s[46:47]
	s_add_i32 s46, s68, s52
	s_mov_b32 m0, s46
	s_nop 0
	global_load_lds_dwordx4 v156, s[44:45]
	s_add_i32 m0, s46, 0x2000
	s_nop 0
	global_load_lds_dwordx4 v160, s[44:45]
	s_mov_b32 m0, s60
	s_nop 0
	global_load_lds_dwordx4 v154, s[42:43]
	s_mov_b32 m0, s61
	s_nop 0
	global_load_lds_dwordx4 v158, s[42:43]
	s_waitcnt vmcnt(8) lgkmcnt(0)
	s_barrier
	v_mfma_f32_16x16x32_bf16 v[62:65], v[130:133], v[184:187], v[62:65]
	v_mfma_f32_16x16x32_bf16 v[62:65], v[134:137], v[188:191], v[62:65]
	v_mfma_f32_16x16x32_bf16 v[58:61], v[138:141], v[184:187], v[58:61]
	v_mfma_f32_16x16x32_bf16 v[58:61], v[142:145], v[188:191], v[58:61]
	v_mfma_f32_16x16x32_bf16 v[46:49], v[130:133], v[192:195], v[46:49]
	v_mfma_f32_16x16x32_bf16 v[46:49], v[134:137], v[196:199], v[46:49]
	v_mfma_f32_16x16x32_bf16 v[42:45], v[138:141], v[192:195], v[42:45]
	v_mfma_f32_16x16x32_bf16 v[42:45], v[142:145], v[196:199], v[42:45]
	v_mfma_f32_16x16x32_bf16 v[30:33], v[130:133], v[210:213], v[30:33]
	v_mfma_f32_16x16x32_bf16 v[30:33], v[134:137], v[214:217], v[30:33]
	v_mfma_f32_16x16x32_bf16 v[26:29], v[138:141], v[210:213], v[26:29]
	v_mfma_f32_16x16x32_bf16 v[26:29], v[142:145], v[214:217], v[26:29]
	v_mfma_f32_16x16x32_bf16 v[14:17], v[130:133], v[218:221], v[14:17]
	v_mfma_f32_16x16x32_bf16 v[14:17], v[134:137], v[222:225], v[14:17]
	v_mfma_f32_16x16x32_bf16 v[10:13], v[138:141], v[218:221], v[10:13]
	v_mfma_f32_16x16x32_bf16 v[10:13], v[142:145], v[222:225], v[10:13]
	v_mfma_f32_16x16x32_bf16 v[54:57], v[146:149], v[184:187], v[54:57]
	v_mfma_f32_16x16x32_bf16 v[54:57], v[150:153], v[188:191], v[54:57]
	v_mfma_f32_16x16x32_bf16 v[50:53], v[176:179], v[184:187], v[50:53]
	v_mfma_f32_16x16x32_bf16 v[50:53], v[180:183], v[188:191], v[50:53]
	v_mfma_f32_16x16x32_bf16 v[38:41], v[146:149], v[192:195], v[38:41]
	v_mfma_f32_16x16x32_bf16 v[38:41], v[150:153], v[196:199], v[38:41]
	v_mfma_f32_16x16x32_bf16 v[34:37], v[176:179], v[192:195], v[34:37]
	v_mfma_f32_16x16x32_bf16 v[34:37], v[180:183], v[196:199], v[34:37]
	v_mfma_f32_16x16x32_bf16 v[22:25], v[146:149], v[210:213], v[22:25]
	v_mfma_f32_16x16x32_bf16 v[22:25], v[150:153], v[214:217], v[22:25]
	v_mfma_f32_16x16x32_bf16 v[18:21], v[176:179], v[210:213], v[18:21]
	v_mfma_f32_16x16x32_bf16 v[18:21], v[180:183], v[214:217], v[18:21]
	v_mfma_f32_16x16x32_bf16 v[6:9], v[146:149], v[218:221], v[6:9]
	v_mfma_f32_16x16x32_bf16 v[6:9], v[150:153], v[222:225], v[6:9]
	v_mfma_f32_16x16x32_bf16 v[2:5], v[176:179], v[218:221], v[2:5]
	v_mfma_f32_16x16x32_bf16 v[2:5], v[180:183], v[222:225], v[2:5]
	s_barrier
	s_add_i32 s66, s66, 2
	s_add_u32 s40, s40, 0x8000
	s_addc_u32 s41, s41, 0
	s_add_u32 s39, s39, 0x8000
	s_addc_u32 s65, s65, 0
	s_cmpk_gt_u32 s66, 0xfd
	s_cbranch_scc0 .LBB0_1292
	s_and_b64 vcc, exec, s[24:25]
	s_cbranch_vccz .LBB0_1295
	s_barrier

.LBB0_1387:
	ds_read_b128 v[62:65], v189
	ds_read_b128 v[66:69], v189 offset:1024
	ds_read_b128 v[74:77], v189 offset:2048
	ds_read_b128 v[78:81], v189 offset:3072
	ds_read_b128 v[146:149], v195
	ds_read_b128 v[150:153], v195 offset:1024
	ds_read_b128 v[154:157], v195 offset:2048
	ds_read_b128 v[158:161], v195 offset:3072
	s_add_u32 s34, s30, 0xfff04000
	s_addc_u32 s35, s31, -1
	s_cmp_eq_u32 s54, 60
	s_cselect_b32 s38, s27, s34
	s_cselect_b32 s39, s21, s35
	s_cselect_b32 s36, s29, s52
	s_cselect_b32 s37, s19, s53
	s_add_u32 s34, s38, 0x4000
	s_addc_u32 s35, s39, 0
	s_add_i32 m0, s40, 0xc000
	ds_read_b128 v[190:193], v197
	ds_read_b128 v[198:201], v197 offset:1024
	ds_read_b128 v[202:205], v197 offset:2048
	ds_read_b128 v[206:209], v197 offset:3072
	ds_read_b128 v[210:213], v197 offset:4096
	ds_read_b128 v[214:217], v197 offset:5120
	ds_read_b128 v[218:221], v197 offset:6144
	ds_read_b128 v[222:225], v197 offset:7168
	global_load_lds_dwordx4 v172, s[30:31]
	s_add_i32 m0, s40, 0xe000
	s_nop 0
	global_load_lds_dwordx4 v174, s[30:31]
	s_waitcnt vmcnt(8) lgkmcnt(0)
	s_barrier
	v_mfma_f32_16x16x32_bf16 v[142:145], v[62:65], v[190:193], v[142:145]
	v_mfma_f32_16x16x32_bf16 v[142:145], v[66:69], v[198:201], v[142:145]
	v_mfma_f32_16x16x32_bf16 v[138:141], v[74:77], v[190:193], v[138:141]
	v_mfma_f32_16x16x32_bf16 v[138:141], v[78:81], v[198:201], v[138:141]
	v_mfma_f32_16x16x32_bf16 v[126:129], v[62:65], v[202:205], v[126:129]
	v_mfma_f32_16x16x32_bf16 v[126:129], v[66:69], v[206:209], v[126:129]
	v_mfma_f32_16x16x32_bf16 v[122:125], v[74:77], v[202:205], v[122:125]
	v_mfma_f32_16x16x32_bf16 v[122:125], v[78:81], v[206:209], v[122:125]
	v_mfma_f32_16x16x32_bf16 v[110:113], v[62:65], v[210:213], v[110:113]
	v_mfma_f32_16x16x32_bf16 v[110:113], v[66:69], v[214:217], v[110:113]
	v_mfma_f32_16x16x32_bf16 v[106:109], v[74:77], v[210:213], v[106:109]
	v_mfma_f32_16x16x32_bf16 v[106:109], v[78:81], v[214:217], v[106:109]
	v_mfma_f32_16x16x32_bf16 v[94:97], v[62:65], v[218:221], v[94:97]
	v_mfma_f32_16x16x32_bf16 v[94:97], v[66:69], v[222:225], v[94:97]
	v_mfma_f32_16x16x32_bf16 v[90:93], v[74:77], v[218:221], v[90:93]
	v_mfma_f32_16x16x32_bf16 v[90:93], v[78:81], v[222:225], v[90:93]
	v_mfma_f32_16x16x32_bf16 v[134:137], v[146:149], v[190:193], v[134:137]
	v_mfma_f32_16x16x32_bf16 v[134:137], v[150:153], v[198:201], v[134:137]
	v_mfma_f32_16x16x32_bf16 v[130:133], v[154:157], v[190:193], v[130:133]
	v_mfma_f32_16x16x32_bf16 v[130:133], v[158:161], v[198:201], v[130:133]
	v_mfma_f32_16x16x32_bf16 v[118:121], v[146:149], v[202:205], v[118:121]
	v_mfma_f32_16x16x32_bf16 v[118:121], v[150:153], v[206:209], v[118:121]
	v_mfma_f32_16x16x32_bf16 v[114:117], v[154:157], v[202:205], v[114:117]
	v_mfma_f32_16x16x32_bf16 v[114:117], v[158:161], v[206:209], v[114:117]
	v_mfma_f32_16x16x32_bf16 v[102:105], v[146:149], v[210:213], v[102:105]
	v_mfma_f32_16x16x32_bf16 v[102:105], v[150:153], v[214:217], v[102:105]
	v_mfma_f32_16x16x32_bf16 v[98:101], v[154:157], v[210:213], v[98:101]
	v_mfma_f32_16x16x32_bf16 v[98:101], v[158:161], v[214:217], v[98:101]
	v_mfma_f32_16x16x32_bf16 v[86:89], v[146:149], v[218:221], v[86:89]
	v_mfma_f32_16x16x32_bf16 v[86:89], v[150:153], v[222:225], v[86:89]
	v_mfma_f32_16x16x32_bf16 v[82:85], v[154:157], v[218:221], v[82:85]
	v_mfma_f32_16x16x32_bf16 v[82:85], v[158:161], v[222:225], v[82:85]
	s_barrier
	s_add_i32 s55, s50, s33
	s_mov_b32 m0, s55
	ds_read_b128 v[190:193], v197 offset:16384
	ds_read_b128 v[198:201], v197 offset:17408
	ds_read_b128 v[202:205], v197 offset:18432
	ds_read_b128 v[206:209], v197 offset:19456
	ds_read_b128 v[210:213], v197 offset:20480
	ds_read_b128 v[214:217], v197 offset:21504
	ds_read_b128 v[218:221], v197 offset:22528
	ds_read_b128 v[222:225], v197 offset:23552
	global_load_lds_dwordx4 v166, s[36:37]
	s_add_i32 m0, s55, 0x2000
	s_add_u32 s56, s36, 0x100000
	s_addc_u32 s57, s37, 0
	s_add_i32 s55, s51, s33
	global_load_lds_dwordx4 v162, s[36:37]
	s_mov_b32 m0, s55
	s_nop 0
	global_load_lds_dwordx4 v166, s[56:57]
	s_add_i32 m0, s55, 0x2000
	s_nop 0
	global_load_lds_dwordx4 v162, s[56:57]
	s_mov_b32 m0, s40
	s_nop 0
	global_load_lds_dwordx4 v168, s[38:39]
	s_mov_b32 m0, s41
	s_nop 0
	global_load_lds_dwordx4 v164, s[38:39]
	s_waitcnt vmcnt(8) lgkmcnt(0)
	s_barrier
	v_mfma_f32_16x16x32_bf16 v[70:73], v[62:65], v[190:193], v[70:73]
	v_mfma_f32_16x16x32_bf16 v[70:73], v[66:69], v[198:201], v[70:73]
	v_mfma_f32_16x16x32_bf16 v[58:61], v[74:77], v[190:193], v[58:61]
	v_mfma_f32_16x16x32_bf16 v[58:61], v[78:81], v[198:201], v[58:61]
	v_mfma_f32_16x16x32_bf16 v[46:49], v[62:65], v[202:205], v[46:49]
	v_mfma_f32_16x16x32_bf16 v[46:49], v[66:69], v[206:209], v[46:49]
	v_mfma_f32_16x16x32_bf16 v[42:45], v[74:77], v[202:205], v[42:45]
	v_mfma_f32_16x16x32_bf16 v[42:45], v[78:81], v[206:209], v[42:45]
	v_mfma_f32_16x16x32_bf16 v[30:33], v[62:65], v[210:213], v[30:33]
	v_mfma_f32_16x16x32_bf16 v[30:33], v[66:69], v[214:217], v[30:33]
	v_mfma_f32_16x16x32_bf16 v[26:29], v[74:77], v[210:213], v[26:29]
	v_mfma_f32_16x16x32_bf16 v[26:29], v[78:81], v[214:217], v[26:29]
	v_mfma_f32_16x16x32_bf16 v[14:17], v[62:65], v[218:221], v[14:17]
	v_mfma_f32_16x16x32_bf16 v[14:17], v[66:69], v[222:225], v[14:17]
	v_mfma_f32_16x16x32_bf16 v[10:13], v[74:77], v[218:221], v[10:13]
	v_mfma_f32_16x16x32_bf16 v[10:13], v[78:81], v[222:225], v[10:13]
	v_mfma_f32_16x16x32_bf16 v[54:57], v[146:149], v[190:193], v[54:57]
	v_mfma_f32_16x16x32_bf16 v[54:57], v[150:153], v[198:201], v[54:57]
	v_mfma_f32_16x16x32_bf16 v[50:53], v[154:157], v[190:193], v[50:53]
	v_mfma_f32_16x16x32_bf16 v[50:53], v[158:161], v[198:201], v[50:53]
	v_mfma_f32_16x16x32_bf16 v[38:41], v[146:149], v[202:205], v[38:41]
	v_mfma_f32_16x16x32_bf16 v[38:41], v[150:153], v[206:209], v[38:41]
	v_mfma_f32_16x16x32_bf16 v[34:37], v[154:157], v[202:205], v[34:37]
	v_mfma_f32_16x16x32_bf16 v[34:37], v[158:161], v[206:209], v[34:37]
	v_mfma_f32_16x16x32_bf16 v[22:25], v[146:149], v[210:213], v[22:25]
	v_mfma_f32_16x16x32_bf16 v[22:25], v[150:153], v[214:217], v[22:25]
	v_mfma_f32_16x16x32_bf16 v[18:21], v[154:157], v[210:213], v[18:21]
	v_mfma_f32_16x16x32_bf16 v[18:21], v[158:161], v[214:217], v[18:21]
	v_mfma_f32_16x16x32_bf16 v[6:9], v[146:149], v[218:221], v[6:9]
	v_mfma_f32_16x16x32_bf16 v[6:9], v[150:153], v[222:225], v[6:9]
	v_mfma_f32_16x16x32_bf16 v[2:5], v[154:157], v[218:221], v[2:5]
	v_mfma_f32_16x16x32_bf16 v[2:5], v[158:161], v[222:225], v[2:5]
	s_barrier
	s_add_i32 s55, 0, 0x18000
	s_add_i32 s56, 0, 0x1c000
	v_add_u32_e32 v78, s55, v187
	v_add_u32_e32 v158, s56, v187
	ds_read_b128 v[62:65], v78
	ds_read_b128 v[66:69], v78 offset:1024
	ds_read_b128 v[74:77], v78 offset:2048
	ds_read_b128 v[78:81], v78 offset:3072
	ds_read_b128 v[146:149], v158
	ds_read_b128 v[150:153], v158 offset:1024
	ds_read_b128 v[154:157], v158 offset:2048
	ds_read_b128 v[158:161], v158 offset:3072
	s_add_u32 s38, s38, 0x100000
	s_addc_u32 s39, s39, 0
	s_mov_b32 m0, s42
	ds_read_b128 v[190:193], v197 offset:32768
	ds_read_b128 v[198:201], v197 offset:33792
	ds_read_b128 v[202:205], v197 offset:34816
	ds_read_b128 v[206:209], v197 offset:35840
	ds_read_b128 v[210:213], v197 offset:36864
	ds_read_b128 v[214:217], v197 offset:37888
	ds_read_b128 v[218:221], v197 offset:38912
	ds_read_b128 v[222:225], v197 offset:39936
	global_load_lds_dwordx4 v168, s[38:39]
	s_mov_b32 m0, s43
	s_nop 0
	global_load_lds_dwordx4 v164, s[38:39]
	s_waitcnt vmcnt(8) lgkmcnt(0)
	s_barrier
	v_mfma_f32_16x16x32_bf16 v[142:145], v[62:65], v[190:193], v[142:145]
	v_mfma_f32_16x16x32_bf16 v[142:145], v[66:69], v[198:201], v[142:145]
	v_mfma_f32_16x16x32_bf16 v[138:141], v[74:77], v[190:193], v[138:141]
	v_mfma_f32_16x16x32_bf16 v[138:141], v[78:81], v[198:201], v[138:141]
	v_mfma_f32_16x16x32_bf16 v[126:129], v[62:65], v[202:205], v[126:129]
	v_mfma_f32_16x16x32_bf16 v[126:129], v[66:69], v[206:209], v[126:129]
	v_mfma_f32_16x16x32_bf16 v[122:125], v[74:77], v[202:205], v[122:125]
	v_mfma_f32_16x16x32_bf16 v[122:125], v[78:81], v[206:209], v[122:125]
	v_mfma_f32_16x16x32_bf16 v[110:113], v[62:65], v[210:213], v[110:113]
	v_mfma_f32_16x16x32_bf16 v[110:113], v[66:69], v[214:217], v[110:113]
	v_mfma_f32_16x16x32_bf16 v[106:109], v[74:77], v[210:213], v[106:109]
	v_mfma_f32_16x16x32_bf16 v[106:109], v[78:81], v[214:217], v[106:109]
	v_mfma_f32_16x16x32_bf16 v[94:97], v[62:65], v[218:221], v[94:97]
	v_mfma_f32_16x16x32_bf16 v[94:97], v[66:69], v[222:225], v[94:97]
	v_mfma_f32_16x16x32_bf16 v[90:93], v[74:77], v[218:221], v[90:93]
	v_mfma_f32_16x16x32_bf16 v[90:93], v[78:81], v[222:225], v[90:93]
	v_mfma_f32_16x16x32_bf16 v[134:137], v[146:149], v[190:193], v[134:137]
	v_mfma_f32_16x16x32_bf16 v[134:137], v[150:153], v[198:201], v[134:137]
	v_mfma_f32_16x16x32_bf16 v[130:133], v[154:157], v[190:193], v[130:133]
	v_mfma_f32_16x16x32_bf16 v[130:133], v[158:161], v[198:201], v[130:133]
	v_mfma_f32_16x16x32_bf16 v[118:121], v[146:149], v[202:205], v[118:121]
	v_mfma_f32_16x16x32_bf16 v[118:121], v[150:153], v[206:209], v[118:121]
	v_mfma_f32_16x16x32_bf16 v[114:117], v[154:157], v[202:205], v[114:117]
	v_mfma_f32_16x16x32_bf16 v[114:117], v[158:161], v[206:209], v[114:117]
	v_mfma_f32_16x16x32_bf16 v[102:105], v[146:149], v[210:213], v[102:105]
	v_mfma_f32_16x16x32_bf16 v[102:105], v[150:153], v[214:217], v[102:105]
	v_mfma_f32_16x16x32_bf16 v[98:101], v[154:157], v[210:213], v[98:101]
	v_mfma_f32_16x16x32_bf16 v[98:101], v[158:161], v[214:217], v[98:101]
	v_mfma_f32_16x16x32_bf16 v[86:89], v[146:149], v[218:221], v[86:89]
	v_mfma_f32_16x16x32_bf16 v[86:89], v[150:153], v[222:225], v[86:89]
	v_mfma_f32_16x16x32_bf16 v[82:85], v[154:157], v[218:221], v[82:85]
	v_mfma_f32_16x16x32_bf16 v[82:85], v[158:161], v[222:225], v[82:85]
	s_barrier
	s_add_u32 s38, s36, 0x4000
	s_addc_u32 s39, s37, 0
	s_add_i32 s55, s55, s33
	s_mov_b32 m0, s55
	ds_read_b128 v[190:193], v197 offset:49152
	ds_read_b128 v[198:201], v197 offset:50176
	ds_read_b128 v[202:205], v197 offset:51200
	ds_read_b128 v[206:209], v197 offset:52224
	ds_read_b128 v[210:213], v197 offset:53248
	ds_read_b128 v[214:217], v197 offset:54272
	ds_read_b128 v[218:221], v197 offset:55296
	ds_read_b128 v[222:225], v197 offset:56320
	global_load_lds_dwordx4 v166, s[38:39]
	s_add_i32 m0, s55, 0x2000
	s_add_u32 s36, s36, 0x104000
	s_addc_u32 s37, s37, 0
	global_load_lds_dwordx4 v162, s[38:39]
	s_add_i32 s38, s56, s33
	s_mov_b32 m0, s38
	s_nop 0
	global_load_lds_dwordx4 v166, s[36:37]
	s_add_i32 m0, s38, 0x2000
	s_nop 0
	global_load_lds_dwordx4 v162, s[36:37]
	s_mov_b32 m0, s46
	s_nop 0
	global_load_lds_dwordx4 v168, s[34:35]
	s_mov_b32 m0, s47
	s_nop 0
	global_load_lds_dwordx4 v164, s[34:35]
	s_waitcnt vmcnt(8) lgkmcnt(0)
	s_barrier
	v_mfma_f32_16x16x32_bf16 v[70:73], v[62:65], v[190:193], v[70:73]
	v_mfma_f32_16x16x32_bf16 v[70:73], v[66:69], v[198:201], v[70:73]
	v_mfma_f32_16x16x32_bf16 v[58:61], v[74:77], v[190:193], v[58:61]
	v_mfma_f32_16x16x32_bf16 v[58:61], v[78:81], v[198:201], v[58:61]
	v_mfma_f32_16x16x32_bf16 v[46:49], v[62:65], v[202:205], v[46:49]
	v_mfma_f32_16x16x32_bf16 v[46:49], v[66:69], v[206:209], v[46:49]
	v_mfma_f32_16x16x32_bf16 v[42:45], v[74:77], v[202:205], v[42:45]
	v_mfma_f32_16x16x32_bf16 v[42:45], v[78:81], v[206:209], v[42:45]
	v_mfma_f32_16x16x32_bf16 v[30:33], v[62:65], v[210:213], v[30:33]
	v_mfma_f32_16x16x32_bf16 v[30:33], v[66:69], v[214:217], v[30:33]
	v_mfma_f32_16x16x32_bf16 v[26:29], v[74:77], v[210:213], v[26:29]
	v_mfma_f32_16x16x32_bf16 v[26:29], v[78:81], v[214:217], v[26:29]
	v_mfma_f32_16x16x32_bf16 v[14:17], v[62:65], v[218:221], v[14:17]
	v_mfma_f32_16x16x32_bf16 v[14:17], v[66:69], v[222:225], v[14:17]
	v_mfma_f32_16x16x32_bf16 v[10:13], v[74:77], v[218:221], v[10:13]
	v_mfma_f32_16x16x32_bf16 v[10:13], v[78:81], v[222:225], v[10:13]
	v_mfma_f32_16x16x32_bf16 v[54:57], v[146:149], v[190:193], v[54:57]
	v_mfma_f32_16x16x32_bf16 v[54:57], v[150:153], v[198:201], v[54:57]
	v_mfma_f32_16x16x32_bf16 v[50:53], v[154:157], v[190:193], v[50:53]
	v_mfma_f32_16x16x32_bf16 v[50:53], v[158:161], v[198:201], v[50:53]
	v_mfma_f32_16x16x32_bf16 v[38:41], v[146:149], v[202:205], v[38:41]
	v_mfma_f32_16x16x32_bf16 v[38:41], v[150:153], v[206:209], v[38:41]
	v_mfma_f32_16x16x32_bf16 v[34:37], v[154:157], v[202:205], v[34:37]
	v_mfma_f32_16x16x32_bf16 v[34:37], v[158:161], v[206:209], v[34:37]
	v_mfma_f32_16x16x32_bf16 v[22:25], v[146:149], v[210:213], v[22:25]
	v_mfma_f32_16x16x32_bf16 v[22:25], v[150:153], v[214:217], v[22:25]
	v_mfma_f32_16x16x32_bf16 v[18:21], v[154:157], v[210:213], v[18:21]
	v_mfma_f32_16x16x32_bf16 v[18:21], v[158:161], v[214:217], v[18:21]
	v_mfma_f32_16x16x32_bf16 v[6:9], v[146:149], v[218:221], v[6:9]
	v_mfma_f32_16x16x32_bf16 v[6:9], v[150:153], v[222:225], v[6:9]
	v_mfma_f32_16x16x32_bf16 v[2:5], v[154:157], v[218:221], v[2:5]
	v_mfma_f32_16x16x32_bf16 v[2:5], v[158:161], v[222:225], v[2:5]
	s_barrier
	s_add_i32 s54, s54, 2
	s_add_u32 s30, s30, 0x8000
	s_addc_u32 s31, s31, 0
	s_add_u32 s52, s52, 0x8000
	s_addc_u32 s53, s53, 0
	s_cmp_gt_u32 s54, 61
	s_cbranch_scc0 .LBB0_1387
	s_and_b64 vcc, exec, s[12:13]
	s_cbranch_vccz .LBB0_1390
	s_barrier
